# v49 + small sample-row GEMM units: all 12 LDS fragment reads of a K-step issued up front, MFMAs behind counted lgkmcnt
# baseline (speedup 1.0000x reference)
; #define LAS __attribute__((address_space(3)))
; #define MFMA32(a, b, c) __builtin_amdgcn_mfma_f32_32x32x16_bf16((a), (b), (c), 0, 0, 0)
; #define GS_STEP(RF, RN, t) do { gs_load<ROWS>(RF, ap, bp, K, ((t) + 4 < nkt) ? (t) + 4 : nkt - 1); \
;         if (wave < ROWS / 32) gs_compute<ROWS>(acc0, acc1, lds + ((t) & 1) * BUF, wave, r, h2); \
;         gs_store<ROWS>(RN, lds + (((t) + 1) & 1) * BUF, soff); \
;         __syncthreads(); } while (0)
; template <int ROWS> DI void gs_load(GsRegs<ROWS>& R, const bf16* ap, const bf16* bp, int K, int kt) {
; #pragma unroll
;     for (int rep = 0; rep < ROWS / 64; ++rep) R.a[rep] = *(const u32x4*)(ap + (size_t)(64 * rep) * K + kt * 64);
;     R.b = *(const u32x4*)(bp + kt * 64);
; }
; template <int ROWS> DI void gs_store(const GsRegs<ROWS>& R, LAS unsigned char* buf, int soff) {
; #pragma unroll
;     for (int rep = 0; rep < ROWS / 64; ++rep) *(LAS u32x4*)(buf + soff + rep * (64 * GS_LD * 2)) = R.a[rep];
;     *(LAS u32x4*)(buf + ROWS * GS_LD * 2 + soff) = R.b;
; }
; template <int ROWS> DI void gs_compute(f32x16& acc0, f32x16& acc1, const LAS unsigned char* ab, int wave, int r, int h2) {
;     const LAS unsigned char* bb = ab + ROWS * GS_LD * 2;
; #pragma unroll
;     for (int s = 0; s < 4; ++s) {
;         const bf16x8 a = *(const LAS bf16x8*)(ab + ((32 * wave + r) * GS_LD + 16 * s + 8 * h2) * 2);
;         const bf16x8 b0 = *(const LAS bf16x8*)(bb + (r * GS_LD + 16 * s + 8 * h2) * 2), b1 = *(const LAS bf16x8*)(bb + ((32 + r) * GS_LD + 16 * s + 8 * h2) * 2);
;         acc0 = MFMA32(a, b0, acc0); acc1 = MFMA32(a, b1, acc1);
;     }
; }
; template <int ROWS, class Epi> DI void gemm_small_unit(LAS unsigned char* lds, const bf16* A, const bf16* Bt, int K, int m0, int n0, int n1, const Epi& E, int tid_, int wave) {
;     ...
; #pragma unroll 1
;     for (int kt = 0; kt < nkt; kt += 4) { GS_STEP(R0, R1, kt); GS_STEP(R1, R2, kt + 1); GS_STEP(R2, R3, kt + 2); GS_STEP(R3, R0, kt + 3); }
.LBB0_164:
	s_cmp_gt_u32 s22, 11
	s_cselect_b64 s[16:17], -1, 0
	s_cmp_lt_u32 s22, 12
	s_cselect_b32 s14, s21, 0x3c0
	s_lshl_b64 s[4:5], s[14:15], 1
	v_lshl_add_u64 v[72:73], v[84:85], 0, s[4:5]
	v_add_co_u32_e32 v76, vcc, 0x20000, v72
	v_lshl_add_u64 v[80:81], v[86:87], 0, s[4:5]
	s_nop 0
	v_addc_co_u32_e32 v77, vcc, 0, v73, vcc
	global_load_dwordx4 v[72:75], v[72:73], off
	s_nop 0
	global_load_dwordx4 v[76:79], v[76:77], off
	v_cndmask_b32_e64 v2, 0, 1, s[12:13]
	global_load_dwordx4 v[80:83], v[80:81], off
	v_cmp_ne_u32_e64 s[4:5], 1, v2
	s_andn2_b64 vcc, exec, s[12:13]
	s_cbranch_vccnz .LBB0_166
	ds_read_b128 v[94:97], v92
	ds_read_b128 v[98:101], v91 offset:18432
	ds_read_b128 v[102:105], v92 offset:32
	ds_read_b128 v[106:109], v91 offset:18464
	ds_read_b128 v[196:199], v91 offset:23040
	ds_read_b128 v[110:113], v91 offset:23072
	ds_read_b128 v[200:203], v92 offset:64
	ds_read_b128 v[204:207], v91 offset:18496
	ds_read_b128 v[208:211], v92 offset:96
	ds_read_b128 v[212:215], v91 offset:18528
	ds_read_b128 v[216:219], v91 offset:23104
	ds_read_b128 v[220:223], v91 offset:23136
	s_waitcnt lgkmcnt(10)
	v_mfma_f32_32x32x16_bf16 v[20:35], v[94:97], v[98:101], v[20:35]
	s_waitcnt lgkmcnt(7)
	v_mfma_f32_32x32x16_bf16 v[4:19], v[94:97], v[196:199], v[4:19]
	v_mfma_f32_32x32x16_bf16 v[20:35], v[102:105], v[106:109], v[20:35]
	s_waitcnt lgkmcnt(6)
	v_mfma_f32_32x32x16_bf16 v[4:19], v[102:105], v[110:113], v[4:19]
	s_waitcnt lgkmcnt(4)
	v_mfma_f32_32x32x16_bf16 v[20:35], v[200:203], v[204:207], v[20:35]
	s_waitcnt lgkmcnt(1)
	v_mfma_f32_32x32x16_bf16 v[4:19], v[200:203], v[216:219], v[4:19]
	v_mfma_f32_32x32x16_bf16 v[20:35], v[208:211], v[212:215], v[20:35]
	s_waitcnt lgkmcnt(0)
	v_mfma_f32_32x32x16_bf16 v[4:19], v[208:211], v[220:223], v[4:19]
.LBB0_166:
	s_min_u32 s14, s22, 10
	s_lshl_b32 s14, s14, 7
	s_waitcnt vmcnt(11)
	ds_write_b128 v90, v[36:39] offset:27648
	s_waitcnt vmcnt(10)
	ds_write_b128 v90, v[40:43] offset:36864
	s_waitcnt vmcnt(9)
	ds_write_b128 v90, v[48:51] offset:46080
	v_lshl_add_u64 v[36:37], v[84:85], 0, s[14:15]
	v_add_co_u32_e32 v40, vcc, 0x20000, v36
	v_lshl_add_u64 v[48:49], v[86:87], 0, s[14:15]
	s_nop 0
	v_addc_co_u32_e32 v41, vcc, 0, v37, vcc
	s_waitcnt lgkmcnt(0)
	s_barrier
	global_load_dwordx4 v[36:39], v[36:37], off offset:640
	s_nop 0
	global_load_dwordx4 v[40:43], v[40:41], off offset:640
	s_and_b64 vcc, exec, s[4:5]
	global_load_dwordx4 v[48:51], v[48:49], off offset:640
	s_cbranch_vccnz .LBB0_168
	ds_read_b128 v[94:97], v92 offset:27648
	ds_read_b128 v[98:101], v91 offset:46080
	ds_read_b128 v[102:105], v92 offset:27680
	ds_read_b128 v[106:109], v91 offset:46112
	ds_read_b128 v[196:199], v91 offset:50688
	ds_read_b128 v[110:113], v91 offset:50720
	ds_read_b128 v[200:203], v92 offset:27712
	ds_read_b128 v[204:207], v91 offset:46144
	ds_read_b128 v[208:211], v92 offset:27744
	ds_read_b128 v[212:215], v91 offset:46176
	ds_read_b128 v[216:219], v91 offset:50752
	ds_read_b128 v[220:223], v91 offset:50784
	s_waitcnt lgkmcnt(10)
	v_mfma_f32_32x32x16_bf16 v[20:35], v[94:97], v[98:101], v[20:35]
	s_waitcnt lgkmcnt(7)
	v_mfma_f32_32x32x16_bf16 v[4:19], v[94:97], v[196:199], v[4:19]
	v_mfma_f32_32x32x16_bf16 v[20:35], v[102:105], v[106:109], v[20:35]
	s_waitcnt lgkmcnt(6)
	v_mfma_f32_32x32x16_bf16 v[4:19], v[102:105], v[110:113], v[4:19]
	s_waitcnt lgkmcnt(4)
	v_mfma_f32_32x32x16_bf16 v[20:35], v[200:203], v[204:207], v[20:35]
	s_waitcnt lgkmcnt(1)
	v_mfma_f32_32x32x16_bf16 v[4:19], v[200:203], v[216:219], v[4:19]
	v_mfma_f32_32x32x16_bf16 v[20:35], v[208:211], v[212:215], v[20:35]
	s_waitcnt lgkmcnt(0)
	v_mfma_f32_32x32x16_bf16 v[4:19], v[208:211], v[220:223], v[4:19]
; #define LAS __attribute__((address_space(3)))
; #define MFMA32(a, b, c) __builtin_amdgcn_mfma_f32_32x32x16_bf16((a), (b), (c), 0, 0, 0)
; #define GS_STEP(RF, RN, t) do { gs_load<ROWS>(RF, ap, bp, K, ((t) + 4 < nkt) ? (t) + 4 : nkt - 1); \
;         if (wave < ROWS / 32) gs_compute<ROWS>(acc0, acc1, lds + ((t) & 1) * BUF, wave, r, h2); \
;         gs_store<ROWS>(RN, lds + (((t) + 1) & 1) * BUF, soff); \
;         __syncthreads(); } while (0)
; template <int ROWS> DI void gs_load(GsRegs<ROWS>& R, const bf16* ap, const bf16* bp, int K, int kt) {
; #pragma unroll
;     for (int rep = 0; rep < ROWS / 64; ++rep) R.a[rep] = *(const u32x4*)(ap + (size_t)(64 * rep) * K + kt * 64);
;     R.b = *(const u32x4*)(bp + kt * 64);
; }
; template <int ROWS> DI void gs_store(const GsRegs<ROWS>& R, LAS unsigned char* buf, int soff) {
; #pragma unroll
;     for (int rep = 0; rep < ROWS / 64; ++rep) *(LAS u32x4*)(buf + soff + rep * (64 * GS_LD * 2)) = R.a[rep];
;     *(LAS u32x4*)(buf + ROWS * GS_LD * 2 + soff) = R.b;
; }
; template <int ROWS> DI void gs_compute(f32x16& acc0, f32x16& acc1, const LAS unsigned char* ab, int wave, int r, int h2) {
;     const LAS unsigned char* bb = ab + ROWS * GS_LD * 2;
; #pragma unroll
;     for (int s = 0; s < 4; ++s) {
;         const bf16x8 a = *(const LAS bf16x8*)(ab + ((32 * wave + r) * GS_LD + 16 * s + 8 * h2) * 2);
;         const bf16x8 b0 = *(const LAS bf16x8*)(bb + (r * GS_LD + 16 * s + 8 * h2) * 2), b1 = *(const LAS bf16x8*)(bb + ((32 + r) * GS_LD + 16 * s + 8 * h2) * 2);
;         acc0 = MFMA32(a, b0, acc0); acc1 = MFMA32(a, b1, acc1);
;     }
; }
; template <int ROWS, class Epi> DI void gemm_small_unit(LAS unsigned char* lds, const bf16* A, const bf16* Bt, int K, int m0, int n0, int n1, const Epi& E, int tid_, int wave) {
;     ...
; #pragma unroll 1
;     for (int kt = 0; kt < nkt; kt += 4) { GS_STEP(R0, R1, kt); GS_STEP(R1, R2, kt + 1); GS_STEP(R2, R3, kt + 2); GS_STEP(R3, R0, kt + 3); }
.LBB0_168:
	s_min_u32 s14, s22, 9
	s_lshl_b32 s14, s14, 7
	s_waitcnt vmcnt(11)
	ds_write_b128 v90, v[44:47]
	s_waitcnt vmcnt(9)
	ds_write_b128 v90, v[56:59] offset:9216
	s_waitcnt vmcnt(7)
	ds_write_b128 v90, v[64:67] offset:18432
	v_lshl_add_u64 v[44:45], v[84:85], 0, s[14:15]
	v_add_co_u32_e32 v56, vcc, 0x20000, v44
	v_lshl_add_u64 v[64:65], v[86:87], 0, s[14:15]
	s_nop 0
	v_addc_co_u32_e32 v57, vcc, 0, v45, vcc
	s_waitcnt lgkmcnt(0)
	s_barrier
	global_load_dwordx4 v[44:47], v[44:45], off offset:768
	s_nop 0
	global_load_dwordx4 v[56:59], v[56:57], off offset:768
	s_and_b64 vcc, exec, s[4:5]
	global_load_dwordx4 v[64:67], v[64:65], off offset:768
	s_cbranch_vccnz .LBB0_170
	ds_read_b128 v[94:97], v92
	ds_read_b128 v[98:101], v91 offset:18432
	ds_read_b128 v[102:105], v92 offset:32
	ds_read_b128 v[106:109], v91 offset:18464
	ds_read_b128 v[196:199], v91 offset:23040
	ds_read_b128 v[110:113], v91 offset:23072
	ds_read_b128 v[200:203], v92 offset:64
	ds_read_b128 v[204:207], v91 offset:18496
	ds_read_b128 v[208:211], v92 offset:96
	ds_read_b128 v[212:215], v91 offset:18528
	ds_read_b128 v[216:219], v91 offset:23104
	ds_read_b128 v[220:223], v91 offset:23136
	s_waitcnt lgkmcnt(10)
	v_mfma_f32_32x32x16_bf16 v[20:35], v[94:97], v[98:101], v[20:35]
	s_waitcnt lgkmcnt(7)
	v_mfma_f32_32x32x16_bf16 v[4:19], v[94:97], v[196:199], v[4:19]
	v_mfma_f32_32x32x16_bf16 v[20:35], v[102:105], v[106:109], v[20:35]
	s_waitcnt lgkmcnt(6)
	v_mfma_f32_32x32x16_bf16 v[4:19], v[102:105], v[110:113], v[4:19]
	s_waitcnt lgkmcnt(4)
	v_mfma_f32_32x32x16_bf16 v[20:35], v[200:203], v[204:207], v[20:35]
	s_waitcnt lgkmcnt(1)
	v_mfma_f32_32x32x16_bf16 v[4:19], v[200:203], v[216:219], v[4:19]
	v_mfma_f32_32x32x16_bf16 v[20:35], v[208:211], v[212:215], v[20:35]
	s_waitcnt lgkmcnt(0)
	v_mfma_f32_32x32x16_bf16 v[4:19], v[208:211], v[220:223], v[4:19]
.LBB0_170:
	s_min_u32 s14, s22, 8
	s_lshl_b32 s14, s14, 7
	ds_write_b128 v90, v[52:55] offset:27648
	ds_write_b128 v90, v[60:63] offset:36864
	s_waitcnt vmcnt(9)
	ds_write_b128 v90, v[68:71] offset:46080
	v_lshl_add_u64 v[52:53], v[84:85], 0, s[14:15]
	v_add_co_u32_e32 v60, vcc, 0x20000, v52
	v_lshl_add_u64 v[68:69], v[86:87], 0, s[14:15]
	s_nop 0
	v_addc_co_u32_e32 v61, vcc, 0, v53, vcc
	s_waitcnt lgkmcnt(0)
	s_barrier
	global_load_dwordx4 v[52:55], v[52:53], off offset:896
	s_nop 0
	global_load_dwordx4 v[60:63], v[60:61], off offset:896
	s_and_b64 vcc, exec, s[4:5]
	global_load_dwordx4 v[68:71], v[68:69], off offset:896
	s_cbranch_vccnz .LBB0_163
	ds_read_b128 v[94:97], v92 offset:27648
	ds_read_b128 v[98:101], v91 offset:46080
	ds_read_b128 v[102:105], v92 offset:27680
	ds_read_b128 v[106:109], v91 offset:46112
	ds_read_b128 v[196:199], v91 offset:50688
	ds_read_b128 v[110:113], v91 offset:50720
	ds_read_b128 v[200:203], v92 offset:27712
	ds_read_b128 v[204:207], v91 offset:46144
	ds_read_b128 v[208:211], v92 offset:27744
	ds_read_b128 v[212:215], v91 offset:46176
	ds_read_b128 v[216:219], v91 offset:50752
	ds_read_b128 v[220:223], v91 offset:50784
	s_waitcnt lgkmcnt(10)
	v_mfma_f32_32x32x16_bf16 v[20:35], v[94:97], v[98:101], v[20:35]
	s_waitcnt lgkmcnt(7)
	v_mfma_f32_32x32x16_bf16 v[4:19], v[94:97], v[196:199], v[4:19]
	v_mfma_f32_32x32x16_bf16 v[20:35], v[102:105], v[106:109], v[20:35]
	s_waitcnt lgkmcnt(6)
	v_mfma_f32_32x32x16_bf16 v[4:19], v[102:105], v[110:113], v[4:19]
	s_waitcnt lgkmcnt(4)
	v_mfma_f32_32x32x16_bf16 v[20:35], v[200:203], v[204:207], v[20:35]
	s_waitcnt lgkmcnt(1)
	v_mfma_f32_32x32x16_bf16 v[4:19], v[200:203], v[216:219], v[4:19]
	v_mfma_f32_32x32x16_bf16 v[20:35], v[208:211], v[212:215], v[20:35]
	s_waitcnt lgkmcnt(0)
	v_mfma_f32_32x32x16_bf16 v[4:19], v[208:211], v[220:223], v[4:19]
	s_branch .LBB0_163

; #define LAS __attribute__((address_space(3)))
; #define MFMA32(a, b, c) __builtin_amdgcn_mfma_f32_32x32x16_bf16((a), (b), (c), 0, 0, 0)
; #define GS_STEP(RF, RN, t) do { gs_load<ROWS>(RF, ap, bp, K, ((t) + 4 < nkt) ? (t) + 4 : nkt - 1); \
;         if (wave < ROWS / 32) gs_compute<ROWS>(acc0, acc1, lds + ((t) & 1) * BUF, wave, r, h2); \
;         gs_store<ROWS>(RN, lds + (((t) + 1) & 1) * BUF, soff); \
;         __syncthreads(); } while (0)
; template <int ROWS> DI void gs_load(GsRegs<ROWS>& R, const bf16* ap, const bf16* bp, int K, int kt) {
; #pragma unroll
;     for (int rep = 0; rep < ROWS / 64; ++rep) R.a[rep] = *(const u32x4*)(ap + (size_t)(64 * rep) * K + kt * 64);
;     R.b = *(const u32x4*)(bp + kt * 64);
; }
; template <int ROWS> DI void gs_store(const GsRegs<ROWS>& R, LAS unsigned char* buf, int soff) {
; #pragma unroll
;     for (int rep = 0; rep < ROWS / 64; ++rep) *(LAS u32x4*)(buf + soff + rep * (64 * GS_LD * 2)) = R.a[rep];
;     *(LAS u32x4*)(buf + ROWS * GS_LD * 2 + soff) = R.b;
; }
; template <int ROWS> DI void gs_compute(f32x16& acc0, f32x16& acc1, const LAS unsigned char* ab, int wave, int r, int h2) {
;     const LAS unsigned char* bb = ab + ROWS * GS_LD * 2;
; #pragma unroll
;     for (int s = 0; s < 4; ++s) {
;         const bf16x8 a = *(const LAS bf16x8*)(ab + ((32 * wave + r) * GS_LD + 16 * s + 8 * h2) * 2);
;         const bf16x8 b0 = *(const LAS bf16x8*)(bb + (r * GS_LD + 16 * s + 8 * h2) * 2), b1 = *(const LAS bf16x8*)(bb + ((32 + r) * GS_LD + 16 * s + 8 * h2) * 2);
;         acc0 = MFMA32(a, b0, acc0); acc1 = MFMA32(a, b1, acc1);
;     }
; }
; template <int ROWS, class Epi> DI void gemm_small_unit(LAS unsigned char* lds, const bf16* A, const bf16* Bt, int K, int m0, int n0, int n1, const Epi& E, int tid_, int wave) {
;     ...
; #pragma unroll 1
;     for (int kt = 0; kt < nkt; kt += 4) { GS_STEP(R0, R1, kt); GS_STEP(R1, R2, kt + 1); GS_STEP(R2, R3, kt + 2); GS_STEP(R3, R0, kt + 3); }
.LBB0_273:
	s_cmp_gt_u32 s23, 27
	s_cselect_b64 s[6:7], -1, 0
	s_cmp_lt_u32 s23, 28
	s_cselect_b32 s16, s22, 0x7c0
	s_lshl_b64 s[36:37], s[16:17], 1
	v_lshl_add_u64 v[4:5], v[74:75], 0, s[36:37]
	v_lshl_add_u64 v[8:9], v[76:77], 0, s[36:37]
	global_load_dwordx4 v[4:7], v[4:5], off
	s_nop 0
	global_load_dwordx4 v[8:11], v[8:9], off
	s_and_b64 vcc, exec, s[4:5]
	s_cbranch_vccnz .LBB0_275
	ds_read_b128 v[12:15], v82
	ds_read_b128 v[84:87], v81 offset:9216
	ds_read_b128 v[196:199], v81 offset:13824
	ds_read_b128 v[200:203], v82 offset:32
	ds_read_b128 v[204:207], v81 offset:9248
	ds_read_b128 v[208:211], v81 offset:13856
	ds_read_b128 v[212:215], v82 offset:64
	ds_read_b128 v[216:219], v81 offset:9280
	ds_read_b128 v[220:223], v81 offset:13888
	ds_read_b128 v[224:227], v82 offset:96
	ds_read_b128 v[228:231], v81 offset:9312
	ds_read_b128 v[232:235], v81 offset:13920
	s_waitcnt lgkmcnt(10)
	v_mfma_f32_32x32x16_bf16 v[34:49], v[12:15], v[84:87], v[34:49]
	s_waitcnt lgkmcnt(9)
	v_mfma_f32_32x32x16_bf16 v[18:33], v[12:15], v[196:199], v[18:33]
	s_waitcnt lgkmcnt(7)
	v_mfma_f32_32x32x16_bf16 v[34:49], v[200:203], v[204:207], v[34:49]
	s_waitcnt lgkmcnt(6)
	v_mfma_f32_32x32x16_bf16 v[18:33], v[200:203], v[208:211], v[18:33]
	s_waitcnt lgkmcnt(4)
	v_mfma_f32_32x32x16_bf16 v[34:49], v[212:215], v[216:219], v[34:49]
	s_waitcnt lgkmcnt(3)
	v_mfma_f32_32x32x16_bf16 v[18:33], v[212:215], v[220:223], v[18:33]
	s_waitcnt lgkmcnt(1)
	v_mfma_f32_32x32x16_bf16 v[34:49], v[224:227], v[228:231], v[34:49]
	s_waitcnt lgkmcnt(0)
	v_mfma_f32_32x32x16_bf16 v[18:33], v[224:227], v[232:235], v[18:33]
.LBB0_275:
	s_min_u32 s16, s23, 26
	s_lshl_b32 s16, s16, 7
	v_lshl_add_u64 v[12:13], v[74:75], 0, s[16:17]
	s_waitcnt vmcnt(7)
	ds_write_b128 v80, v[50:53] offset:18432
	s_waitcnt vmcnt(6)
	ds_write_b128 v80, v[54:57] offset:27648
	s_waitcnt lgkmcnt(0)
	s_barrier
	v_lshl_add_u64 v[14:15], v[76:77], 0, s[16:17]
	global_load_dwordx4 v[50:53], v[12:13], off offset:640
	global_load_dwordx4 v[54:57], v[14:15], off offset:640
	s_and_b64 vcc, exec, s[4:5]
	s_cbranch_vccnz .LBB0_277
	ds_read_b128 v[12:15], v82 offset:18432
	ds_read_b128 v[84:87], v81 offset:27648
	ds_read_b128 v[196:199], v81 offset:32256
	ds_read_b128 v[200:203], v82 offset:18464
	ds_read_b128 v[204:207], v81 offset:27680
	ds_read_b128 v[208:211], v81 offset:32288
	ds_read_b128 v[212:215], v82 offset:18496
	ds_read_b128 v[216:219], v81 offset:27712
	ds_read_b128 v[220:223], v81 offset:32320
	ds_read_b128 v[224:227], v82 offset:18528
	ds_read_b128 v[228:231], v81 offset:27744
	ds_read_b128 v[232:235], v81 offset:32352
	s_waitcnt lgkmcnt(10)
	v_mfma_f32_32x32x16_bf16 v[34:49], v[12:15], v[84:87], v[34:49]
	s_waitcnt lgkmcnt(9)
	v_mfma_f32_32x32x16_bf16 v[18:33], v[12:15], v[196:199], v[18:33]
	s_waitcnt lgkmcnt(7)
	v_mfma_f32_32x32x16_bf16 v[34:49], v[200:203], v[204:207], v[34:49]
	s_waitcnt lgkmcnt(6)
	v_mfma_f32_32x32x16_bf16 v[18:33], v[200:203], v[208:211], v[18:33]
	s_waitcnt lgkmcnt(4)
	v_mfma_f32_32x32x16_bf16 v[34:49], v[212:215], v[216:219], v[34:49]
	s_waitcnt lgkmcnt(3)
	v_mfma_f32_32x32x16_bf16 v[18:33], v[212:215], v[220:223], v[18:33]
	s_waitcnt lgkmcnt(1)
	v_mfma_f32_32x32x16_bf16 v[34:49], v[224:227], v[228:231], v[34:49]
	s_waitcnt lgkmcnt(0)
	v_mfma_f32_32x32x16_bf16 v[18:33], v[224:227], v[232:235], v[18:33]
.LBB0_277:
	s_min_u32 s16, s23, 25
	s_lshl_b32 s16, s16, 7
	v_lshl_add_u64 v[12:13], v[74:75], 0, s[16:17]
	s_waitcnt vmcnt(7)
	ds_write_b128 v80, v[58:61]
	s_waitcnt vmcnt(5)
	ds_write_b128 v80, v[66:69] offset:9216
	s_waitcnt lgkmcnt(0)
	s_barrier
	v_lshl_add_u64 v[14:15], v[76:77], 0, s[16:17]
	global_load_dwordx4 v[58:61], v[12:13], off offset:768
	global_load_dwordx4 v[66:69], v[14:15], off offset:768
	s_and_b64 vcc, exec, s[4:5]
	s_cbranch_vccnz .LBB0_279
	ds_read_b128 v[12:15], v82
	ds_read_b128 v[84:87], v81 offset:9216
	ds_read_b128 v[196:199], v81 offset:13824
	ds_read_b128 v[200:203], v82 offset:32
	ds_read_b128 v[204:207], v81 offset:9248
	ds_read_b128 v[208:211], v81 offset:13856
	ds_read_b128 v[212:215], v82 offset:64
	ds_read_b128 v[216:219], v81 offset:9280
	ds_read_b128 v[220:223], v81 offset:13888
	ds_read_b128 v[224:227], v82 offset:96
	ds_read_b128 v[228:231], v81 offset:9312
	ds_read_b128 v[232:235], v81 offset:13920
	s_waitcnt lgkmcnt(10)
	v_mfma_f32_32x32x16_bf16 v[34:49], v[12:15], v[84:87], v[34:49]
	s_waitcnt lgkmcnt(9)
	v_mfma_f32_32x32x16_bf16 v[18:33], v[12:15], v[196:199], v[18:33]
	s_waitcnt lgkmcnt(7)
	v_mfma_f32_32x32x16_bf16 v[34:49], v[200:203], v[204:207], v[34:49]
	s_waitcnt lgkmcnt(6)
	v_mfma_f32_32x32x16_bf16 v[18:33], v[200:203], v[208:211], v[18:33]
	s_waitcnt lgkmcnt(4)
	v_mfma_f32_32x32x16_bf16 v[34:49], v[212:215], v[216:219], v[34:49]
	s_waitcnt lgkmcnt(3)
	v_mfma_f32_32x32x16_bf16 v[18:33], v[212:215], v[220:223], v[18:33]
	s_waitcnt lgkmcnt(1)
	v_mfma_f32_32x32x16_bf16 v[34:49], v[224:227], v[228:231], v[34:49]
	s_waitcnt lgkmcnt(0)
	v_mfma_f32_32x32x16_bf16 v[18:33], v[224:227], v[232:235], v[18:33]
.LBB0_279:
	s_min_u32 s16, s23, 24
	s_lshl_b32 s16, s16, 7
	v_lshl_add_u64 v[12:13], v[74:75], 0, s[16:17]
	ds_write_b128 v80, v[62:65] offset:18432
	s_waitcnt vmcnt(6)
	ds_write_b128 v80, v[70:73] offset:27648
	s_waitcnt lgkmcnt(0)
	s_barrier
	v_lshl_add_u64 v[14:15], v[76:77], 0, s[16:17]
	global_load_dwordx4 v[62:65], v[12:13], off offset:896
	global_load_dwordx4 v[70:73], v[14:15], off offset:896
	s_and_b64 vcc, exec, s[4:5]
	s_cbranch_vccnz .LBB0_272
	ds_read_b128 v[12:15], v82 offset:18432
	ds_read_b128 v[84:87], v81 offset:27648
	ds_read_b128 v[196:199], v81 offset:32256
	ds_read_b128 v[200:203], v82 offset:18464
	ds_read_b128 v[204:207], v81 offset:27680
	ds_read_b128 v[208:211], v81 offset:32288
	ds_read_b128 v[212:215], v82 offset:18496
	ds_read_b128 v[216:219], v81 offset:27712
	ds_read_b128 v[220:223], v81 offset:32320
	ds_read_b128 v[224:227], v82 offset:18528
	ds_read_b128 v[228:231], v81 offset:27744
	ds_read_b128 v[232:235], v81 offset:32352
	s_waitcnt lgkmcnt(10)
	v_mfma_f32_32x32x16_bf16 v[34:49], v[12:15], v[84:87], v[34:49]
	s_waitcnt lgkmcnt(9)
	v_mfma_f32_32x32x16_bf16 v[18:33], v[12:15], v[196:199], v[18:33]
	s_waitcnt lgkmcnt(7)
	v_mfma_f32_32x32x16_bf16 v[34:49], v[200:203], v[204:207], v[34:49]
	s_waitcnt lgkmcnt(6)
	v_mfma_f32_32x32x16_bf16 v[18:33], v[200:203], v[208:211], v[18:33]
	s_waitcnt lgkmcnt(4)
	v_mfma_f32_32x32x16_bf16 v[34:49], v[212:215], v[216:219], v[34:49]
	s_waitcnt lgkmcnt(3)
	v_mfma_f32_32x32x16_bf16 v[18:33], v[212:215], v[220:223], v[18:33]
	s_waitcnt lgkmcnt(1)
	v_mfma_f32_32x32x16_bf16 v[34:49], v[224:227], v[228:231], v[34:49]
	s_waitcnt lgkmcnt(0)
	v_mfma_f32_32x32x16_bf16 v[18:33], v[224:227], v[232:235], v[18:33]
	s_branch .LBB0_272

; #define LAS __attribute__((address_space(3)))
; #define MFMA32(a, b, c) __builtin_amdgcn_mfma_f32_32x32x16_bf16((a), (b), (c), 0, 0, 0)
; #define GS_STEP(RF, RN, t) do { gs_load<ROWS>(RF, ap, bp, K, ((t) + 4 < nkt) ? (t) + 4 : nkt - 1); \
;         if (wave < ROWS / 32) gs_compute<ROWS>(acc0, acc1, lds + ((t) & 1) * BUF, wave, r, h2); \
;         gs_store<ROWS>(RN, lds + (((t) + 1) & 1) * BUF, soff); \
;         __syncthreads(); } while (0)
; template <int ROWS> DI void gs_load(GsRegs<ROWS>& R, const bf16* ap, const bf16* bp, int K, int kt) {
; #pragma unroll
;     for (int rep = 0; rep < ROWS / 64; ++rep) R.a[rep] = *(const u32x4*)(ap + (size_t)(64 * rep) * K + kt * 64);
;     R.b = *(const u32x4*)(bp + kt * 64);
; }
; template <int ROWS> DI void gs_store(const GsRegs<ROWS>& R, LAS unsigned char* buf, int soff) {
; #pragma unroll
;     for (int rep = 0; rep < ROWS / 64; ++rep) *(LAS u32x4*)(buf + soff + rep * (64 * GS_LD * 2)) = R.a[rep];
;     *(LAS u32x4*)(buf + ROWS * GS_LD * 2 + soff) = R.b;
; }
; template <int ROWS> DI void gs_compute(f32x16& acc0, f32x16& acc1, const LAS unsigned char* ab, int wave, int r, int h2) {
;     const LAS unsigned char* bb = ab + ROWS * GS_LD * 2;
; #pragma unroll
;     for (int s = 0; s < 4; ++s) {
;         const bf16x8 a = *(const LAS bf16x8*)(ab + ((32 * wave + r) * GS_LD + 16 * s + 8 * h2) * 2);
;         const bf16x8 b0 = *(const LAS bf16x8*)(bb + (r * GS_LD + 16 * s + 8 * h2) * 2), b1 = *(const LAS bf16x8*)(bb + ((32 + r) * GS_LD + 16 * s + 8 * h2) * 2);
;         acc0 = MFMA32(a, b0, acc0); acc1 = MFMA32(a, b1, acc1);
;     }
; }
; template <int ROWS, class Epi> DI void gemm_small_unit(LAS unsigned char* lds, const bf16* A, const bf16* Bt, int K, int m0, int n0, int n1, const Epi& E, int tid_, int wave) {
;     ...
; #pragma unroll 1
;     for (int kt = 0; kt < nkt; kt += 4) { GS_STEP(R0, R1, kt); GS_STEP(R1, R2, kt + 1); GS_STEP(R2, R3, kt + 2); GS_STEP(R3, R0, kt + 3); }
.LBB0_387:
	s_cmp_gt_u32 s34, 11
	s_cselect_b64 s[18:19], -1, 0
	s_cmp_lt_u32 s34, 12
	s_cselect_b32 s14, s23, 0x3c0
	s_lshl_b64 s[4:5], s[14:15], 1
	v_lshl_add_u64 v[4:5], v[86:87], 0, s[4:5]
	v_add_co_u32_e32 v8, vcc, 0x20000, v4
	v_lshl_add_u64 v[12:13], v[88:89], 0, s[4:5]
	s_nop 0
	v_addc_co_u32_e32 v9, vcc, 0, v5, vcc
	global_load_dwordx4 v[4:7], v[4:5], off
	s_nop 0
	global_load_dwordx4 v[8:11], v[8:9], off
	v_cndmask_b32_e64 v2, 0, 1, s[12:13]
	global_load_dwordx4 v[12:15], v[12:13], off
	v_cmp_ne_u32_e64 s[4:5], 1, v2
	s_andn2_b64 vcc, exec, s[12:13]
	s_cbranch_vccnz .LBB0_389
	ds_read_b128 v[96:99], v94
	ds_read_b128 v[100:103], v93 offset:18432
	ds_read_b128 v[104:107], v94 offset:32
	ds_read_b128 v[108:111], v93 offset:18464
	ds_read_b128 v[196:199], v93 offset:23040
	ds_read_b128 v[112:115], v93 offset:23072
	ds_read_b128 v[200:203], v94 offset:64
	ds_read_b128 v[204:207], v93 offset:18496
	ds_read_b128 v[208:211], v94 offset:96
	ds_read_b128 v[212:215], v93 offset:18528
	ds_read_b128 v[216:219], v93 offset:23104
	ds_read_b128 v[220:223], v93 offset:23136
	s_waitcnt lgkmcnt(10)
	v_mfma_f32_32x32x16_bf16 v[18:33], v[96:99], v[100:103], v[18:33]
	s_waitcnt lgkmcnt(7)
	v_mfma_f32_32x32x16_bf16 v[34:49], v[96:99], v[196:199], v[34:49]
	v_mfma_f32_32x32x16_bf16 v[18:33], v[104:107], v[108:111], v[18:33]
	s_waitcnt lgkmcnt(6)
	v_mfma_f32_32x32x16_bf16 v[34:49], v[104:107], v[112:115], v[34:49]
	s_waitcnt lgkmcnt(4)
	v_mfma_f32_32x32x16_bf16 v[18:33], v[200:203], v[204:207], v[18:33]
	s_waitcnt lgkmcnt(1)
	v_mfma_f32_32x32x16_bf16 v[34:49], v[200:203], v[216:219], v[34:49]
	v_mfma_f32_32x32x16_bf16 v[18:33], v[208:211], v[212:215], v[18:33]
	s_waitcnt lgkmcnt(0)
	v_mfma_f32_32x32x16_bf16 v[34:49], v[208:211], v[220:223], v[34:49]
.LBB0_389:
	s_min_u32 s14, s34, 10
	s_lshl_b32 s14, s14, 7
	v_lshl_add_u64 v[16:17], v[86:87], 0, s[14:15]
	s_waitcnt vmcnt(11)
	ds_write_b128 v92, v[50:53] offset:27648
	s_waitcnt vmcnt(10)
	ds_write_b128 v92, v[54:57] offset:36864
	s_waitcnt vmcnt(9)
	ds_write_b128 v92, v[62:65] offset:46080
	v_add_co_u32_e32 v54, vcc, 0x20000, v16
	s_waitcnt lgkmcnt(0)
	s_nop 0
	v_addc_co_u32_e32 v55, vcc, 0, v17, vcc
	s_barrier
	global_load_dwordx4 v[50:53], v[16:17], off offset:640
	s_nop 0
	global_load_dwordx4 v[54:57], v[54:55], off offset:640
	v_lshl_add_u64 v[16:17], v[88:89], 0, s[14:15]
	global_load_dwordx4 v[62:65], v[16:17], off offset:640
	s_and_b64 vcc, exec, s[4:5]
	s_cbranch_vccnz .LBB0_391
	ds_read_b128 v[96:99], v94 offset:27648
	ds_read_b128 v[100:103], v93 offset:46080
	ds_read_b128 v[104:107], v94 offset:27680
	ds_read_b128 v[108:111], v93 offset:46112
	ds_read_b128 v[196:199], v93 offset:50688
	ds_read_b128 v[112:115], v93 offset:50720
	ds_read_b128 v[200:203], v94 offset:27712
	ds_read_b128 v[204:207], v93 offset:46144
	ds_read_b128 v[208:211], v94 offset:27744
	ds_read_b128 v[212:215], v93 offset:46176
	ds_read_b128 v[216:219], v93 offset:50752
	ds_read_b128 v[220:223], v93 offset:50784
	s_waitcnt lgkmcnt(10)
	v_mfma_f32_32x32x16_bf16 v[18:33], v[96:99], v[100:103], v[18:33]
	s_waitcnt lgkmcnt(7)
	v_mfma_f32_32x32x16_bf16 v[34:49], v[96:99], v[196:199], v[34:49]
	v_mfma_f32_32x32x16_bf16 v[18:33], v[104:107], v[108:111], v[18:33]
	s_waitcnt lgkmcnt(6)
	v_mfma_f32_32x32x16_bf16 v[34:49], v[104:107], v[112:115], v[34:49]
	s_waitcnt lgkmcnt(4)
	v_mfma_f32_32x32x16_bf16 v[18:33], v[200:203], v[204:207], v[18:33]
	s_waitcnt lgkmcnt(1)
	v_mfma_f32_32x32x16_bf16 v[34:49], v[200:203], v[216:219], v[34:49]
	v_mfma_f32_32x32x16_bf16 v[18:33], v[208:211], v[212:215], v[18:33]
	s_waitcnt lgkmcnt(0)
	v_mfma_f32_32x32x16_bf16 v[34:49], v[208:211], v[220:223], v[34:49]
; #define LAS __attribute__((address_space(3)))
; #define MFMA32(a, b, c) __builtin_amdgcn_mfma_f32_32x32x16_bf16((a), (b), (c), 0, 0, 0)
; #define GS_STEP(RF, RN, t) do { gs_load<ROWS>(RF, ap, bp, K, ((t) + 4 < nkt) ? (t) + 4 : nkt - 1); \
;         if (wave < ROWS / 32) gs_compute<ROWS>(acc0, acc1, lds + ((t) & 1) * BUF, wave, r, h2); \
;         gs_store<ROWS>(RN, lds + (((t) + 1) & 1) * BUF, soff); \
;         __syncthreads(); } while (0)
; template <int ROWS> DI void gs_load(GsRegs<ROWS>& R, const bf16* ap, const bf16* bp, int K, int kt) {
; #pragma unroll
;     for (int rep = 0; rep < ROWS / 64; ++rep) R.a[rep] = *(const u32x4*)(ap + (size_t)(64 * rep) * K + kt * 64);
;     R.b = *(const u32x4*)(bp + kt * 64);
; }
; template <int ROWS> DI void gs_store(const GsRegs<ROWS>& R, LAS unsigned char* buf, int soff) {
; #pragma unroll
;     for (int rep = 0; rep < ROWS / 64; ++rep) *(LAS u32x4*)(buf + soff + rep * (64 * GS_LD * 2)) = R.a[rep];
;     *(LAS u32x4*)(buf + ROWS * GS_LD * 2 + soff) = R.b;
; }
; template <int ROWS> DI void gs_compute(f32x16& acc0, f32x16& acc1, const LAS unsigned char* ab, int wave, int r, int h2) {
;     const LAS unsigned char* bb = ab + ROWS * GS_LD * 2;
; #pragma unroll
;     for (int s = 0; s < 4; ++s) {
;         const bf16x8 a = *(const LAS bf16x8*)(ab + ((32 * wave + r) * GS_LD + 16 * s + 8 * h2) * 2);
;         const bf16x8 b0 = *(const LAS bf16x8*)(bb + (r * GS_LD + 16 * s + 8 * h2) * 2), b1 = *(const LAS bf16x8*)(bb + ((32 + r) * GS_LD + 16 * s + 8 * h2) * 2);
;         acc0 = MFMA32(a, b0, acc0); acc1 = MFMA32(a, b1, acc1);
;     }
; }
; template <int ROWS, class Epi> DI void gemm_small_unit(LAS unsigned char* lds, const bf16* A, const bf16* Bt, int K, int m0, int n0, int n1, const Epi& E, int tid_, int wave) {
;     ...
; #pragma unroll 1
;     for (int kt = 0; kt < nkt; kt += 4) { GS_STEP(R0, R1, kt); GS_STEP(R1, R2, kt + 1); GS_STEP(R2, R3, kt + 2); GS_STEP(R3, R0, kt + 3); }
.LBB0_391:
	s_min_u32 s14, s34, 9
	s_lshl_b32 s14, s14, 7
	v_lshl_add_u64 v[16:17], v[86:87], 0, s[14:15]
	s_waitcnt vmcnt(11)
	ds_write_b128 v92, v[58:61]
	s_waitcnt vmcnt(10)
	ds_write_b128 v92, v[78:81] offset:9216
	s_waitcnt vmcnt(9)
	ds_write_b128 v92, v[70:73] offset:18432
	v_add_co_u32_e32 v70, vcc, 0x20000, v16
	s_waitcnt lgkmcnt(0)
	s_barrier
	v_addc_co_u32_e32 v71, vcc, 0, v17, vcc
	global_load_dwordx4 v[58:61], v[16:17], off offset:768
	global_load_dwordx4 v[78:81], v[70:71], off offset:768
	v_lshl_add_u64 v[16:17], v[88:89], 0, s[14:15]
	global_load_dwordx4 v[70:73], v[16:17], off offset:768
	s_and_b64 vcc, exec, s[4:5]
	s_cbranch_vccnz .LBB0_393
	ds_read_b128 v[96:99], v94
	ds_read_b128 v[100:103], v93 offset:18432
	ds_read_b128 v[104:107], v94 offset:32
	ds_read_b128 v[108:111], v93 offset:18464
	ds_read_b128 v[196:199], v93 offset:23040
	ds_read_b128 v[112:115], v93 offset:23072
	ds_read_b128 v[200:203], v94 offset:64
	ds_read_b128 v[204:207], v93 offset:18496
	ds_read_b128 v[208:211], v94 offset:96
	ds_read_b128 v[212:215], v93 offset:18528
	ds_read_b128 v[216:219], v93 offset:23104
	ds_read_b128 v[220:223], v93 offset:23136
	s_waitcnt lgkmcnt(10)
	v_mfma_f32_32x32x16_bf16 v[18:33], v[96:99], v[100:103], v[18:33]
	s_waitcnt lgkmcnt(7)
	v_mfma_f32_32x32x16_bf16 v[34:49], v[96:99], v[196:199], v[34:49]
	v_mfma_f32_32x32x16_bf16 v[18:33], v[104:107], v[108:111], v[18:33]
	s_waitcnt lgkmcnt(6)
	v_mfma_f32_32x32x16_bf16 v[34:49], v[104:107], v[112:115], v[34:49]
	s_waitcnt lgkmcnt(4)
	v_mfma_f32_32x32x16_bf16 v[18:33], v[200:203], v[204:207], v[18:33]
	s_waitcnt lgkmcnt(1)
	v_mfma_f32_32x32x16_bf16 v[34:49], v[200:203], v[216:219], v[34:49]
	v_mfma_f32_32x32x16_bf16 v[18:33], v[208:211], v[212:215], v[18:33]
	s_waitcnt lgkmcnt(0)
	v_mfma_f32_32x32x16_bf16 v[34:49], v[208:211], v[220:223], v[34:49]
.LBB0_393:
	s_min_u32 s14, s34, 8
	s_lshl_b32 s14, s14, 7
	v_lshl_add_u64 v[16:17], v[86:87], 0, s[14:15]
	s_waitcnt vmcnt(11)
	ds_write_b128 v92, v[66:69] offset:27648
	s_waitcnt vmcnt(10)
	ds_write_b128 v92, v[82:85] offset:36864
	s_waitcnt vmcnt(9)
	ds_write_b128 v92, v[74:77] offset:46080
	v_add_co_u32_e32 v74, vcc, 0x20000, v16
	s_waitcnt lgkmcnt(0)
	s_barrier
	v_addc_co_u32_e32 v75, vcc, 0, v17, vcc
	global_load_dwordx4 v[66:69], v[16:17], off offset:896
	global_load_dwordx4 v[82:85], v[74:75], off offset:896
	v_lshl_add_u64 v[16:17], v[88:89], 0, s[14:15]
	global_load_dwordx4 v[74:77], v[16:17], off offset:896
	s_and_b64 vcc, exec, s[4:5]
	s_cbranch_vccnz .LBB0_386
	ds_read_b128 v[96:99], v94 offset:27648
	ds_read_b128 v[100:103], v93 offset:46080
	ds_read_b128 v[104:107], v94 offset:27680
	ds_read_b128 v[108:111], v93 offset:46112
	ds_read_b128 v[196:199], v93 offset:50688
	ds_read_b128 v[112:115], v93 offset:50720
	ds_read_b128 v[200:203], v94 offset:27712
	ds_read_b128 v[204:207], v93 offset:46144
	ds_read_b128 v[208:211], v94 offset:27744
	ds_read_b128 v[212:215], v93 offset:46176
	ds_read_b128 v[216:219], v93 offset:50752
	ds_read_b128 v[220:223], v93 offset:50784
	s_waitcnt lgkmcnt(10)
	v_mfma_f32_32x32x16_bf16 v[18:33], v[96:99], v[100:103], v[18:33]
	s_waitcnt lgkmcnt(7)
	v_mfma_f32_32x32x16_bf16 v[34:49], v[96:99], v[196:199], v[34:49]
	v_mfma_f32_32x32x16_bf16 v[18:33], v[104:107], v[108:111], v[18:33]
	s_waitcnt lgkmcnt(6)
	v_mfma_f32_32x32x16_bf16 v[34:49], v[104:107], v[112:115], v[34:49]
	s_waitcnt lgkmcnt(4)
	v_mfma_f32_32x32x16_bf16 v[18:33], v[200:203], v[204:207], v[18:33]
	s_waitcnt lgkmcnt(1)
	v_mfma_f32_32x32x16_bf16 v[34:49], v[200:203], v[216:219], v[34:49]
	v_mfma_f32_32x32x16_bf16 v[18:33], v[208:211], v[212:215], v[18:33]
	s_waitcnt lgkmcnt(0)
	v_mfma_f32_32x32x16_bf16 v[34:49], v[208:211], v[220:223], v[34:49]
	s_branch .LBB0_386

; #define LAS __attribute__((address_space(3)))
; #define MFMA32(a, b, c) __builtin_amdgcn_mfma_f32_32x32x16_bf16((a), (b), (c), 0, 0, 0)
; #define GS_STEP(RF, RN, t) do { gs_load<ROWS>(RF, ap, bp, K, ((t) + 4 < nkt) ? (t) + 4 : nkt - 1); \
;         if (wave < ROWS / 32) gs_compute<ROWS>(acc0, acc1, lds + ((t) & 1) * BUF, wave, r, h2); \
;         gs_store<ROWS>(RN, lds + (((t) + 1) & 1) * BUF, soff); \
;         __syncthreads(); } while (0)
; template <int ROWS> DI void gs_load(GsRegs<ROWS>& R, const bf16* ap, const bf16* bp, int K, int kt) {
; #pragma unroll
;     for (int rep = 0; rep < ROWS / 64; ++rep) R.a[rep] = *(const u32x4*)(ap + (size_t)(64 * rep) * K + kt * 64);
;     R.b = *(const u32x4*)(bp + kt * 64);
; }
; template <int ROWS> DI void gs_store(const GsRegs<ROWS>& R, LAS unsigned char* buf, int soff) {
; #pragma unroll
;     for (int rep = 0; rep < ROWS / 64; ++rep) *(LAS u32x4*)(buf + soff + rep * (64 * GS_LD * 2)) = R.a[rep];
;     *(LAS u32x4*)(buf + ROWS * GS_LD * 2 + soff) = R.b;
; }
; template <int ROWS> DI void gs_compute(f32x16& acc0, f32x16& acc1, const LAS unsigned char* ab, int wave, int r, int h2) {
;     const LAS unsigned char* bb = ab + ROWS * GS_LD * 2;
; #pragma unroll
;     for (int s = 0; s < 4; ++s) {
;         const bf16x8 a = *(const LAS bf16x8*)(ab + ((32 * wave + r) * GS_LD + 16 * s + 8 * h2) * 2);
;         const bf16x8 b0 = *(const LAS bf16x8*)(bb + (r * GS_LD + 16 * s + 8 * h2) * 2), b1 = *(const LAS bf16x8*)(bb + ((32 + r) * GS_LD + 16 * s + 8 * h2) * 2);
;         acc0 = MFMA32(a, b0, acc0); acc1 = MFMA32(a, b1, acc1);
;     }
; }
; template <int ROWS, class Epi> DI void gemm_small_unit(LAS unsigned char* lds, const bf16* A, const bf16* Bt, int K, int m0, int n0, int n1, const Epi& E, int tid_, int wave) {
;     ...
; #pragma unroll 1
;     for (int kt = 0; kt < nkt; kt += 4) { GS_STEP(R0, R1, kt); GS_STEP(R1, R2, kt + 1); GS_STEP(R2, R3, kt + 2); GS_STEP(R3, R0, kt + 3); }
.LBB0_837:
	s_cmp_gt_u32 s21, 11
	s_cselect_b64 s[16:17], -1, 0
	s_cmp_lt_u32 s21, 12
	s_cselect_b32 s14, s20, 0x3c0
	s_lshl_b64 s[22:23], s[14:15], 1
	v_lshl_add_u64 v[4:5], v[76:77], 0, s[22:23]
	v_lshl_add_u64 v[8:9], v[78:79], 0, s[22:23]
	global_load_dwordx4 v[4:7], v[4:5], off
	s_nop 0
	global_load_dwordx4 v[8:11], v[8:9], off
	s_and_b64 vcc, exec, s[0:1]
	s_cbranch_vccnz .LBB0_839
	ds_read_b128 v[12:15], v82
	ds_read_b128 v[84:87], v81 offset:9216
	ds_read_b128 v[88:91], v82 offset:32
	ds_read_b128 v[92:95], v81 offset:9248
	ds_read_b128 v[196:199], v81 offset:13824
	ds_read_b128 v[96:99], v81 offset:13856
	ds_read_b128 v[200:203], v82 offset:64
	ds_read_b128 v[204:207], v81 offset:9280
	ds_read_b128 v[208:211], v82 offset:96
	ds_read_b128 v[212:215], v81 offset:9312
	ds_read_b128 v[216:219], v81 offset:13888
	ds_read_b128 v[220:223], v81 offset:13920
	s_waitcnt lgkmcnt(10)
	v_mfma_f32_32x32x16_bf16 v[34:49], v[12:15], v[84:87], v[34:49]
	s_waitcnt lgkmcnt(7)
	v_mfma_f32_32x32x16_bf16 v[18:33], v[12:15], v[196:199], v[18:33]
	v_mfma_f32_32x32x16_bf16 v[34:49], v[88:91], v[92:95], v[34:49]
	s_waitcnt lgkmcnt(6)
	v_mfma_f32_32x32x16_bf16 v[18:33], v[88:91], v[96:99], v[18:33]
	s_waitcnt lgkmcnt(4)
	v_mfma_f32_32x32x16_bf16 v[34:49], v[200:203], v[204:207], v[34:49]
	s_waitcnt lgkmcnt(1)
	v_mfma_f32_32x32x16_bf16 v[18:33], v[200:203], v[216:219], v[18:33]
	v_mfma_f32_32x32x16_bf16 v[34:49], v[208:211], v[212:215], v[34:49]
	s_waitcnt lgkmcnt(0)
	v_mfma_f32_32x32x16_bf16 v[18:33], v[208:211], v[220:223], v[18:33]
.LBB0_839:
	s_min_u32 s14, s21, 10
	s_lshl_b32 s14, s14, 7
	v_lshl_add_u64 v[12:13], v[76:77], 0, s[14:15]
	s_waitcnt vmcnt(7)
	ds_write_b128 v80, v[50:53] offset:18432
	s_waitcnt vmcnt(6)
	ds_write_b128 v80, v[54:57] offset:27648
	s_waitcnt lgkmcnt(0)
	s_barrier
	v_lshl_add_u64 v[14:15], v[78:79], 0, s[14:15]
	global_load_dwordx4 v[50:53], v[12:13], off offset:640
	global_load_dwordx4 v[54:57], v[14:15], off offset:640
	s_and_b64 vcc, exec, s[0:1]
	s_cbranch_vccnz .LBB0_841
	ds_read_b128 v[12:15], v82 offset:18432
	ds_read_b128 v[84:87], v81 offset:27648
	ds_read_b128 v[88:91], v82 offset:18464
	ds_read_b128 v[92:95], v81 offset:27680
	ds_read_b128 v[196:199], v81 offset:32256
	ds_read_b128 v[96:99], v81 offset:32288
	ds_read_b128 v[200:203], v82 offset:18496
	ds_read_b128 v[204:207], v81 offset:27712
	ds_read_b128 v[208:211], v82 offset:18528
	ds_read_b128 v[212:215], v81 offset:27744
	ds_read_b128 v[216:219], v81 offset:32320
	ds_read_b128 v[220:223], v81 offset:32352
	s_waitcnt lgkmcnt(10)
	v_mfma_f32_32x32x16_bf16 v[34:49], v[12:15], v[84:87], v[34:49]
	s_waitcnt lgkmcnt(7)
	v_mfma_f32_32x32x16_bf16 v[18:33], v[12:15], v[196:199], v[18:33]
	v_mfma_f32_32x32x16_bf16 v[34:49], v[88:91], v[92:95], v[34:49]
	s_waitcnt lgkmcnt(6)
	v_mfma_f32_32x32x16_bf16 v[18:33], v[88:91], v[96:99], v[18:33]
	s_waitcnt lgkmcnt(4)
	v_mfma_f32_32x32x16_bf16 v[34:49], v[200:203], v[204:207], v[34:49]
	s_waitcnt lgkmcnt(1)
	v_mfma_f32_32x32x16_bf16 v[18:33], v[200:203], v[216:219], v[18:33]
	v_mfma_f32_32x32x16_bf16 v[34:49], v[208:211], v[212:215], v[34:49]
	s_waitcnt lgkmcnt(0)
	v_mfma_f32_32x32x16_bf16 v[18:33], v[208:211], v[220:223], v[18:33]
.LBB0_841:
	s_min_u32 s14, s21, 9
	s_lshl_b32 s14, s14, 7
	v_lshl_add_u64 v[12:13], v[76:77], 0, s[14:15]
	s_waitcnt vmcnt(7)
	ds_write_b128 v80, v[58:61]
	s_waitcnt vmcnt(5)
	ds_write_b128 v80, v[66:69] offset:9216
	s_waitcnt lgkmcnt(0)
	s_barrier
	v_lshl_add_u64 v[14:15], v[78:79], 0, s[14:15]
	global_load_dwordx4 v[58:61], v[12:13], off offset:768
	global_load_dwordx4 v[66:69], v[14:15], off offset:768
	s_and_b64 vcc, exec, s[0:1]
	s_cbranch_vccnz .LBB0_843
	ds_read_b128 v[12:15], v82
	ds_read_b128 v[84:87], v81 offset:9216
	ds_read_b128 v[88:91], v82 offset:32
	ds_read_b128 v[92:95], v81 offset:9248
	ds_read_b128 v[196:199], v81 offset:13824
	ds_read_b128 v[96:99], v81 offset:13856
	ds_read_b128 v[200:203], v82 offset:64
	ds_read_b128 v[204:207], v81 offset:9280
	ds_read_b128 v[208:211], v82 offset:96
	ds_read_b128 v[212:215], v81 offset:9312
	ds_read_b128 v[216:219], v81 offset:13888
	ds_read_b128 v[220:223], v81 offset:13920
	s_waitcnt lgkmcnt(10)
	v_mfma_f32_32x32x16_bf16 v[34:49], v[12:15], v[84:87], v[34:49]
	s_waitcnt lgkmcnt(7)
	v_mfma_f32_32x32x16_bf16 v[18:33], v[12:15], v[196:199], v[18:33]
	v_mfma_f32_32x32x16_bf16 v[34:49], v[88:91], v[92:95], v[34:49]
	s_waitcnt lgkmcnt(6)
	v_mfma_f32_32x32x16_bf16 v[18:33], v[88:91], v[96:99], v[18:33]
	s_waitcnt lgkmcnt(4)
	v_mfma_f32_32x32x16_bf16 v[34:49], v[200:203], v[204:207], v[34:49]
	s_waitcnt lgkmcnt(1)
	v_mfma_f32_32x32x16_bf16 v[18:33], v[200:203], v[216:219], v[18:33]
	v_mfma_f32_32x32x16_bf16 v[34:49], v[208:211], v[212:215], v[34:49]
	s_waitcnt lgkmcnt(0)
	v_mfma_f32_32x32x16_bf16 v[18:33], v[208:211], v[220:223], v[18:33]
.LBB0_843:
	s_min_u32 s14, s21, 8
	s_lshl_b32 s14, s14, 7
	v_lshl_add_u64 v[12:13], v[76:77], 0, s[14:15]
	ds_write_b128 v80, v[62:65] offset:18432
	s_waitcnt vmcnt(6)
	ds_write_b128 v80, v[70:73] offset:27648
	s_waitcnt lgkmcnt(0)
	s_barrier
	v_lshl_add_u64 v[14:15], v[78:79], 0, s[14:15]
	global_load_dwordx4 v[62:65], v[12:13], off offset:896
	global_load_dwordx4 v[70:73], v[14:15], off offset:896
	s_and_b64 vcc, exec, s[0:1]
	s_cbranch_vccnz .LBB0_836
	ds_read_b128 v[12:15], v82 offset:18432
	ds_read_b128 v[84:87], v81 offset:27648
	ds_read_b128 v[88:91], v82 offset:18464
	ds_read_b128 v[92:95], v81 offset:27680
	ds_read_b128 v[196:199], v81 offset:32256
	ds_read_b128 v[96:99], v81 offset:32288
	ds_read_b128 v[200:203], v82 offset:18496
	ds_read_b128 v[204:207], v81 offset:27712
	ds_read_b128 v[208:211], v82 offset:18528
	ds_read_b128 v[212:215], v81 offset:27744
	ds_read_b128 v[216:219], v81 offset:32320
	ds_read_b128 v[220:223], v81 offset:32352
	s_waitcnt lgkmcnt(10)
	v_mfma_f32_32x32x16_bf16 v[34:49], v[12:15], v[84:87], v[34:49]
	s_waitcnt lgkmcnt(7)
	v_mfma_f32_32x32x16_bf16 v[18:33], v[12:15], v[196:199], v[18:33]
	v_mfma_f32_32x32x16_bf16 v[34:49], v[88:91], v[92:95], v[34:49]
	s_waitcnt lgkmcnt(6)
	v_mfma_f32_32x32x16_bf16 v[18:33], v[88:91], v[96:99], v[18:33]
	s_waitcnt lgkmcnt(4)
	v_mfma_f32_32x32x16_bf16 v[34:49], v[200:203], v[204:207], v[34:49]
	s_waitcnt lgkmcnt(1)
	v_mfma_f32_32x32x16_bf16 v[18:33], v[200:203], v[216:219], v[18:33]
	v_mfma_f32_32x32x16_bf16 v[34:49], v[208:211], v[212:215], v[34:49]
	s_waitcnt lgkmcnt(0)
	v_mfma_f32_32x32x16_bf16 v[18:33], v[208:211], v[220:223], v[18:33]
	s_branch .LBB0_836

; #define LAS __attribute__((address_space(3)))
; #define MFMA32(a, b, c) __builtin_amdgcn_mfma_f32_32x32x16_bf16((a), (b), (c), 0, 0, 0)
; #define GS_STEP(RF, RN, t) do { gs_load<ROWS>(RF, ap, bp, K, ((t) + 4 < nkt) ? (t) + 4 : nkt - 1); \
;         if (wave < ROWS / 32) gs_compute<ROWS>(acc0, acc1, lds + ((t) & 1) * BUF, wave, r, h2); \
;         gs_store<ROWS>(RN, lds + (((t) + 1) & 1) * BUF, soff); \
;         __syncthreads(); } while (0)
; template <int ROWS> DI void gs_load(GsRegs<ROWS>& R, const bf16* ap, const bf16* bp, int K, int kt) {
; #pragma unroll
;     for (int rep = 0; rep < ROWS / 64; ++rep) R.a[rep] = *(const u32x4*)(ap + (size_t)(64 * rep) * K + kt * 64);
;     R.b = *(const u32x4*)(bp + kt * 64);
; }
; template <int ROWS> DI void gs_store(const GsRegs<ROWS>& R, LAS unsigned char* buf, int soff) {
; #pragma unroll
;     for (int rep = 0; rep < ROWS / 64; ++rep) *(LAS u32x4*)(buf + soff + rep * (64 * GS_LD * 2)) = R.a[rep];
;     *(LAS u32x4*)(buf + ROWS * GS_LD * 2 + soff) = R.b;
; }
; template <int ROWS> DI void gs_compute(f32x16& acc0, f32x16& acc1, const LAS unsigned char* ab, int wave, int r, int h2) {
;     const LAS unsigned char* bb = ab + ROWS * GS_LD * 2;
; #pragma unroll
;     for (int s = 0; s < 4; ++s) {
;         const bf16x8 a = *(const LAS bf16x8*)(ab + ((32 * wave + r) * GS_LD + 16 * s + 8 * h2) * 2);
;         const bf16x8 b0 = *(const LAS bf16x8*)(bb + (r * GS_LD + 16 * s + 8 * h2) * 2), b1 = *(const LAS bf16x8*)(bb + ((32 + r) * GS_LD + 16 * s + 8 * h2) * 2);
;         acc0 = MFMA32(a, b0, acc0); acc1 = MFMA32(a, b1, acc1);
;     }
; }
; template <int ROWS, class Epi> DI void gemm_small_unit(LAS unsigned char* lds, const bf16* A, const bf16* Bt, int K, int m0, int n0, int n1, const Epi& E, int tid_, int wave) {
;     ...
; #pragma unroll 1
;     for (int kt = 0; kt < nkt; kt += 4) { GS_STEP(R0, R1, kt); GS_STEP(R1, R2, kt + 1); GS_STEP(R2, R3, kt + 2); GS_STEP(R3, R0, kt + 3); }
.LBB0_958:
	s_cmp_gt_u32 s21, 11
	s_cselect_b64 s[14:15], -1, 0
	s_cmp_lt_u32 s21, 12
	s_cselect_b32 s12, s20, 0x3c0
	s_lshl_b64 s[0:1], s[12:13], 1
	v_lshl_add_u64 v[72:73], v[84:85], 0, s[0:1]
	v_add_co_u32_e32 v76, vcc, 0x20000, v72
	v_lshl_add_u64 v[80:81], v[86:87], 0, s[0:1]
	s_nop 0
	v_addc_co_u32_e32 v77, vcc, 0, v73, vcc
	global_load_dwordx4 v[72:75], v[72:73], off
	s_nop 0
	global_load_dwordx4 v[76:79], v[76:77], off
	v_cndmask_b32_e64 v2, 0, 1, s[10:11]
	global_load_dwordx4 v[80:83], v[80:81], off
	v_cmp_ne_u32_e64 s[0:1], 1, v2
	s_andn2_b64 vcc, exec, s[10:11]
	s_cbranch_vccnz .LBB0_960
	ds_read_b128 v[94:97], v92
	ds_read_b128 v[98:101], v91 offset:18432
	ds_read_b128 v[102:105], v92 offset:32
	ds_read_b128 v[106:109], v91 offset:18464
	ds_read_b128 v[196:199], v91 offset:23040
	ds_read_b128 v[110:113], v91 offset:23072
	ds_read_b128 v[200:203], v92 offset:64
	ds_read_b128 v[204:207], v91 offset:18496
	ds_read_b128 v[208:211], v92 offset:96
	ds_read_b128 v[212:215], v91 offset:18528
	ds_read_b128 v[216:219], v91 offset:23104
	ds_read_b128 v[220:223], v91 offset:23136
	s_waitcnt lgkmcnt(10)
	v_mfma_f32_32x32x16_bf16 v[20:35], v[94:97], v[98:101], v[20:35]
	s_waitcnt lgkmcnt(7)
	v_mfma_f32_32x32x16_bf16 v[4:19], v[94:97], v[196:199], v[4:19]
	v_mfma_f32_32x32x16_bf16 v[20:35], v[102:105], v[106:109], v[20:35]
	s_waitcnt lgkmcnt(6)
	v_mfma_f32_32x32x16_bf16 v[4:19], v[102:105], v[110:113], v[4:19]
	s_waitcnt lgkmcnt(4)
	v_mfma_f32_32x32x16_bf16 v[20:35], v[200:203], v[204:207], v[20:35]
	s_waitcnt lgkmcnt(1)
	v_mfma_f32_32x32x16_bf16 v[4:19], v[200:203], v[216:219], v[4:19]
	v_mfma_f32_32x32x16_bf16 v[20:35], v[208:211], v[212:215], v[20:35]
	s_waitcnt lgkmcnt(0)
	v_mfma_f32_32x32x16_bf16 v[4:19], v[208:211], v[220:223], v[4:19]
.LBB0_960:
	s_min_u32 s12, s21, 10
	s_lshl_b32 s12, s12, 7
	s_waitcnt vmcnt(11)
	ds_write_b128 v90, v[36:39] offset:27648
	s_waitcnt vmcnt(10)
	ds_write_b128 v90, v[40:43] offset:36864
	s_waitcnt vmcnt(9)
	ds_write_b128 v90, v[48:51] offset:46080
	v_lshl_add_u64 v[36:37], v[84:85], 0, s[12:13]
	v_add_co_u32_e32 v40, vcc, 0x20000, v36
	v_lshl_add_u64 v[48:49], v[86:87], 0, s[12:13]
	s_nop 0
	v_addc_co_u32_e32 v41, vcc, 0, v37, vcc
	s_waitcnt lgkmcnt(0)
	s_barrier
	global_load_dwordx4 v[36:39], v[36:37], off offset:640
	s_nop 0
	global_load_dwordx4 v[40:43], v[40:41], off offset:640
	s_and_b64 vcc, exec, s[0:1]
	global_load_dwordx4 v[48:51], v[48:49], off offset:640
	s_cbranch_vccnz .LBB0_962
	ds_read_b128 v[94:97], v92 offset:27648
	ds_read_b128 v[98:101], v91 offset:46080
	ds_read_b128 v[102:105], v92 offset:27680
	ds_read_b128 v[106:109], v91 offset:46112
	ds_read_b128 v[196:199], v91 offset:50688
	ds_read_b128 v[110:113], v91 offset:50720
	ds_read_b128 v[200:203], v92 offset:27712
	ds_read_b128 v[204:207], v91 offset:46144
	ds_read_b128 v[208:211], v92 offset:27744
	ds_read_b128 v[212:215], v91 offset:46176
	ds_read_b128 v[216:219], v91 offset:50752
	ds_read_b128 v[220:223], v91 offset:50784
	s_waitcnt lgkmcnt(10)
	v_mfma_f32_32x32x16_bf16 v[20:35], v[94:97], v[98:101], v[20:35]
	s_waitcnt lgkmcnt(7)
	v_mfma_f32_32x32x16_bf16 v[4:19], v[94:97], v[196:199], v[4:19]
	v_mfma_f32_32x32x16_bf16 v[20:35], v[102:105], v[106:109], v[20:35]
	s_waitcnt lgkmcnt(6)
	v_mfma_f32_32x32x16_bf16 v[4:19], v[102:105], v[110:113], v[4:19]
	s_waitcnt lgkmcnt(4)
	v_mfma_f32_32x32x16_bf16 v[20:35], v[200:203], v[204:207], v[20:35]
	s_waitcnt lgkmcnt(1)
	v_mfma_f32_32x32x16_bf16 v[4:19], v[200:203], v[216:219], v[4:19]
	v_mfma_f32_32x32x16_bf16 v[20:35], v[208:211], v[212:215], v[20:35]
	s_waitcnt lgkmcnt(0)
	v_mfma_f32_32x32x16_bf16 v[4:19], v[208:211], v[220:223], v[4:19]
; #define LAS __attribute__((address_space(3)))
; #define MFMA32(a, b, c) __builtin_amdgcn_mfma_f32_32x32x16_bf16((a), (b), (c), 0, 0, 0)
; #define GS_STEP(RF, RN, t) do { gs_load<ROWS>(RF, ap, bp, K, ((t) + 4 < nkt) ? (t) + 4 : nkt - 1); \
;         if (wave < ROWS / 32) gs_compute<ROWS>(acc0, acc1, lds + ((t) & 1) * BUF, wave, r, h2); \
;         gs_store<ROWS>(RN, lds + (((t) + 1) & 1) * BUF, soff); \
;         __syncthreads(); } while (0)
; template <int ROWS> DI void gs_load(GsRegs<ROWS>& R, const bf16* ap, const bf16* bp, int K, int kt) {
; #pragma unroll
;     for (int rep = 0; rep < ROWS / 64; ++rep) R.a[rep] = *(const u32x4*)(ap + (size_t)(64 * rep) * K + kt * 64);
;     R.b = *(const u32x4*)(bp + kt * 64);
; }
; template <int ROWS> DI void gs_store(const GsRegs<ROWS>& R, LAS unsigned char* buf, int soff) {
; #pragma unroll
;     for (int rep = 0; rep < ROWS / 64; ++rep) *(LAS u32x4*)(buf + soff + rep * (64 * GS_LD * 2)) = R.a[rep];
;     *(LAS u32x4*)(buf + ROWS * GS_LD * 2 + soff) = R.b;
; }
; template <int ROWS> DI void gs_compute(f32x16& acc0, f32x16& acc1, const LAS unsigned char* ab, int wave, int r, int h2) {
;     const LAS unsigned char* bb = ab + ROWS * GS_LD * 2;
; #pragma unroll
;     for (int s = 0; s < 4; ++s) {
;         const bf16x8 a = *(const LAS bf16x8*)(ab + ((32 * wave + r) * GS_LD + 16 * s + 8 * h2) * 2);
;         const bf16x8 b0 = *(const LAS bf16x8*)(bb + (r * GS_LD + 16 * s + 8 * h2) * 2), b1 = *(const LAS bf16x8*)(bb + ((32 + r) * GS_LD + 16 * s + 8 * h2) * 2);
;         acc0 = MFMA32(a, b0, acc0); acc1 = MFMA32(a, b1, acc1);
;     }
; }
; template <int ROWS, class Epi> DI void gemm_small_unit(LAS unsigned char* lds, const bf16* A, const bf16* Bt, int K, int m0, int n0, int n1, const Epi& E, int tid_, int wave) {
;     ...
; #pragma unroll 1
;     for (int kt = 0; kt < nkt; kt += 4) { GS_STEP(R0, R1, kt); GS_STEP(R1, R2, kt + 1); GS_STEP(R2, R3, kt + 2); GS_STEP(R3, R0, kt + 3); }
.LBB0_962:
	s_min_u32 s12, s21, 9
	s_lshl_b32 s12, s12, 7
	s_waitcnt vmcnt(11)
	ds_write_b128 v90, v[44:47]
	s_waitcnt vmcnt(9)
	ds_write_b128 v90, v[56:59] offset:9216
	s_waitcnt vmcnt(7)
	ds_write_b128 v90, v[64:67] offset:18432
	v_lshl_add_u64 v[44:45], v[84:85], 0, s[12:13]
	v_add_co_u32_e32 v56, vcc, 0x20000, v44
	v_lshl_add_u64 v[64:65], v[86:87], 0, s[12:13]
	s_nop 0
	v_addc_co_u32_e32 v57, vcc, 0, v45, vcc
	s_waitcnt lgkmcnt(0)
	s_barrier
	global_load_dwordx4 v[44:47], v[44:45], off offset:768
	s_nop 0
	global_load_dwordx4 v[56:59], v[56:57], off offset:768
	s_and_b64 vcc, exec, s[0:1]
	global_load_dwordx4 v[64:67], v[64:65], off offset:768
	s_cbranch_vccnz .LBB0_964
	ds_read_b128 v[94:97], v92
	ds_read_b128 v[98:101], v91 offset:18432
	ds_read_b128 v[102:105], v92 offset:32
	ds_read_b128 v[106:109], v91 offset:18464
	ds_read_b128 v[196:199], v91 offset:23040
	ds_read_b128 v[110:113], v91 offset:23072
	ds_read_b128 v[200:203], v92 offset:64
	ds_read_b128 v[204:207], v91 offset:18496
	ds_read_b128 v[208:211], v92 offset:96
	ds_read_b128 v[212:215], v91 offset:18528
	ds_read_b128 v[216:219], v91 offset:23104
	ds_read_b128 v[220:223], v91 offset:23136
	s_waitcnt lgkmcnt(10)
	v_mfma_f32_32x32x16_bf16 v[20:35], v[94:97], v[98:101], v[20:35]
	s_waitcnt lgkmcnt(7)
	v_mfma_f32_32x32x16_bf16 v[4:19], v[94:97], v[196:199], v[4:19]
	v_mfma_f32_32x32x16_bf16 v[20:35], v[102:105], v[106:109], v[20:35]
	s_waitcnt lgkmcnt(6)
	v_mfma_f32_32x32x16_bf16 v[4:19], v[102:105], v[110:113], v[4:19]
	s_waitcnt lgkmcnt(4)
	v_mfma_f32_32x32x16_bf16 v[20:35], v[200:203], v[204:207], v[20:35]
	s_waitcnt lgkmcnt(1)
	v_mfma_f32_32x32x16_bf16 v[4:19], v[200:203], v[216:219], v[4:19]
	v_mfma_f32_32x32x16_bf16 v[20:35], v[208:211], v[212:215], v[20:35]
	s_waitcnt lgkmcnt(0)
	v_mfma_f32_32x32x16_bf16 v[4:19], v[208:211], v[220:223], v[4:19]
.LBB0_964:
	s_min_u32 s12, s21, 8
	s_lshl_b32 s12, s12, 7
	ds_write_b128 v90, v[52:55] offset:27648
	ds_write_b128 v90, v[60:63] offset:36864
	s_waitcnt vmcnt(9)
	ds_write_b128 v90, v[68:71] offset:46080
	v_lshl_add_u64 v[52:53], v[84:85], 0, s[12:13]
	v_add_co_u32_e32 v60, vcc, 0x20000, v52
	v_lshl_add_u64 v[68:69], v[86:87], 0, s[12:13]
	s_nop 0
	v_addc_co_u32_e32 v61, vcc, 0, v53, vcc
	s_waitcnt lgkmcnt(0)
	s_barrier
	global_load_dwordx4 v[52:55], v[52:53], off offset:896
	s_nop 0
	global_load_dwordx4 v[60:63], v[60:61], off offset:896
	s_and_b64 vcc, exec, s[0:1]
	global_load_dwordx4 v[68:71], v[68:69], off offset:896
	s_cbranch_vccnz .LBB0_957
	ds_read_b128 v[94:97], v92 offset:27648
	ds_read_b128 v[98:101], v91 offset:46080
	ds_read_b128 v[102:105], v92 offset:27680
	ds_read_b128 v[106:109], v91 offset:46112
	ds_read_b128 v[196:199], v91 offset:50688
	ds_read_b128 v[110:113], v91 offset:50720
	ds_read_b128 v[200:203], v92 offset:27712
	ds_read_b128 v[204:207], v91 offset:46144
	ds_read_b128 v[208:211], v92 offset:27744
	ds_read_b128 v[212:215], v91 offset:46176
	ds_read_b128 v[216:219], v91 offset:50752
	ds_read_b128 v[220:223], v91 offset:50784
	s_waitcnt lgkmcnt(10)
	v_mfma_f32_32x32x16_bf16 v[20:35], v[94:97], v[98:101], v[20:35]
	s_waitcnt lgkmcnt(7)
	v_mfma_f32_32x32x16_bf16 v[4:19], v[94:97], v[196:199], v[4:19]
	v_mfma_f32_32x32x16_bf16 v[20:35], v[102:105], v[106:109], v[20:35]
	s_waitcnt lgkmcnt(6)
	v_mfma_f32_32x32x16_bf16 v[4:19], v[102:105], v[110:113], v[4:19]
	s_waitcnt lgkmcnt(4)
	v_mfma_f32_32x32x16_bf16 v[20:35], v[200:203], v[204:207], v[20:35]
	s_waitcnt lgkmcnt(1)
	v_mfma_f32_32x32x16_bf16 v[4:19], v[200:203], v[216:219], v[4:19]
	v_mfma_f32_32x32x16_bf16 v[20:35], v[208:211], v[212:215], v[20:35]
	s_waitcnt lgkmcnt(0)
	v_mfma_f32_32x32x16_bf16 v[4:19], v[208:211], v[220:223], v[4:19]
	s_branch .LBB0_957

; #define LAS __attribute__((address_space(3)))
; #define MFMA32(a, b, c) __builtin_amdgcn_mfma_f32_32x32x16_bf16((a), (b), (c), 0, 0, 0)
; #define GS_STEP(RF, RN, t) do { gs_load<ROWS>(RF, ap, bp, K, ((t) + 4 < nkt) ? (t) + 4 : nkt - 1); \
;         if (wave < ROWS / 32) gs_compute<ROWS>(acc0, acc1, lds + ((t) & 1) * BUF, wave, r, h2); \
;         gs_store<ROWS>(RN, lds + (((t) + 1) & 1) * BUF, soff); \
;         __syncthreads(); } while (0)
; template <int ROWS> DI void gs_load(GsRegs<ROWS>& R, const bf16* ap, const bf16* bp, int K, int kt) {
; #pragma unroll
;     for (int rep = 0; rep < ROWS / 64; ++rep) R.a[rep] = *(const u32x4*)(ap + (size_t)(64 * rep) * K + kt * 64);
;     R.b = *(const u32x4*)(bp + kt * 64);
; }
; template <int ROWS> DI void gs_store(const GsRegs<ROWS>& R, LAS unsigned char* buf, int soff) {
; #pragma unroll
;     for (int rep = 0; rep < ROWS / 64; ++rep) *(LAS u32x4*)(buf + soff + rep * (64 * GS_LD * 2)) = R.a[rep];
;     *(LAS u32x4*)(buf + ROWS * GS_LD * 2 + soff) = R.b;
; }
; template <int ROWS> DI void gs_compute(f32x16& acc0, f32x16& acc1, const LAS unsigned char* ab, int wave, int r, int h2) {
;     const LAS unsigned char* bb = ab + ROWS * GS_LD * 2;
; #pragma unroll
;     for (int s = 0; s < 4; ++s) {
;         const bf16x8 a = *(const LAS bf16x8*)(ab + ((32 * wave + r) * GS_LD + 16 * s + 8 * h2) * 2);
;         const bf16x8 b0 = *(const LAS bf16x8*)(bb + (r * GS_LD + 16 * s + 8 * h2) * 2), b1 = *(const LAS bf16x8*)(bb + ((32 + r) * GS_LD + 16 * s + 8 * h2) * 2);
;         acc0 = MFMA32(a, b0, acc0); acc1 = MFMA32(a, b1, acc1);
;     }
; }
; template <int ROWS, class Epi> DI void gemm_small_unit(LAS unsigned char* lds, const bf16* A, const bf16* Bt, int K, int m0, int n0, int n1, const Epi& E, int tid_, int wave) {
;     ...
; #pragma unroll 1
;     for (int kt = 0; kt < nkt; kt += 4) { GS_STEP(R0, R1, kt); GS_STEP(R1, R2, kt + 1); GS_STEP(R2, R3, kt + 2); GS_STEP(R3, R0, kt + 3); }
.LBB0_1067:
	s_cmp_gt_u32 s21, 27
	s_cselect_b64 s[16:17], -1, 0
	s_cmp_lt_u32 s21, 28
	s_cselect_b32 s14, s20, 0x7c0
	s_lshl_b64 s[22:23], s[14:15], 1
	v_lshl_add_u64 v[4:5], v[76:77], 0, s[22:23]
	v_lshl_add_u64 v[8:9], v[78:79], 0, s[22:23]
	global_load_dwordx4 v[4:7], v[4:5], off
	s_nop 0
	global_load_dwordx4 v[8:11], v[8:9], off
	s_and_b64 vcc, exec, s[0:1]
	s_cbranch_vccnz .LBB0_1069
	ds_read_b128 v[12:15], v82
	ds_read_b128 v[84:87], v81 offset:9216
	ds_read_b128 v[88:91], v82 offset:32
	ds_read_b128 v[92:95], v81 offset:9248
	ds_read_b128 v[196:199], v81 offset:13824
	ds_read_b128 v[96:99], v81 offset:13856
	ds_read_b128 v[200:203], v82 offset:64
	ds_read_b128 v[204:207], v81 offset:9280
	ds_read_b128 v[208:211], v82 offset:96
	ds_read_b128 v[212:215], v81 offset:9312
	ds_read_b128 v[216:219], v81 offset:13888
	ds_read_b128 v[220:223], v81 offset:13920
	s_waitcnt lgkmcnt(10)
	v_mfma_f32_32x32x16_bf16 v[34:49], v[12:15], v[84:87], v[34:49]
	s_waitcnt lgkmcnt(7)
	v_mfma_f32_32x32x16_bf16 v[18:33], v[12:15], v[196:199], v[18:33]
	v_mfma_f32_32x32x16_bf16 v[34:49], v[88:91], v[92:95], v[34:49]
	s_waitcnt lgkmcnt(6)
	v_mfma_f32_32x32x16_bf16 v[18:33], v[88:91], v[96:99], v[18:33]
	s_waitcnt lgkmcnt(4)
	v_mfma_f32_32x32x16_bf16 v[34:49], v[200:203], v[204:207], v[34:49]
	s_waitcnt lgkmcnt(1)
	v_mfma_f32_32x32x16_bf16 v[18:33], v[200:203], v[216:219], v[18:33]
	v_mfma_f32_32x32x16_bf16 v[34:49], v[208:211], v[212:215], v[34:49]
	s_waitcnt lgkmcnt(0)
	v_mfma_f32_32x32x16_bf16 v[18:33], v[208:211], v[220:223], v[18:33]
.LBB0_1069:
	s_min_u32 s14, s21, 26
	s_lshl_b32 s14, s14, 7
	v_lshl_add_u64 v[12:13], v[76:77], 0, s[14:15]
	s_waitcnt vmcnt(7)
	ds_write_b128 v80, v[50:53] offset:18432
	s_waitcnt vmcnt(6)
	ds_write_b128 v80, v[54:57] offset:27648
	s_waitcnt lgkmcnt(0)
	s_barrier
	v_lshl_add_u64 v[14:15], v[78:79], 0, s[14:15]
	global_load_dwordx4 v[50:53], v[12:13], off offset:640
	global_load_dwordx4 v[54:57], v[14:15], off offset:640
	s_and_b64 vcc, exec, s[0:1]
	s_cbranch_vccnz .LBB0_1071
	ds_read_b128 v[12:15], v82 offset:18432
	ds_read_b128 v[84:87], v81 offset:27648
	ds_read_b128 v[88:91], v82 offset:18464
	ds_read_b128 v[92:95], v81 offset:27680
	ds_read_b128 v[196:199], v81 offset:32256
	ds_read_b128 v[96:99], v81 offset:32288
	ds_read_b128 v[200:203], v82 offset:18496
	ds_read_b128 v[204:207], v81 offset:27712
	ds_read_b128 v[208:211], v82 offset:18528
	ds_read_b128 v[212:215], v81 offset:27744
	ds_read_b128 v[216:219], v81 offset:32320
	ds_read_b128 v[220:223], v81 offset:32352
	s_waitcnt lgkmcnt(10)
	v_mfma_f32_32x32x16_bf16 v[34:49], v[12:15], v[84:87], v[34:49]
	s_waitcnt lgkmcnt(7)
	v_mfma_f32_32x32x16_bf16 v[18:33], v[12:15], v[196:199], v[18:33]
	v_mfma_f32_32x32x16_bf16 v[34:49], v[88:91], v[92:95], v[34:49]
	s_waitcnt lgkmcnt(6)
	v_mfma_f32_32x32x16_bf16 v[18:33], v[88:91], v[96:99], v[18:33]
	s_waitcnt lgkmcnt(4)
	v_mfma_f32_32x32x16_bf16 v[34:49], v[200:203], v[204:207], v[34:49]
	s_waitcnt lgkmcnt(1)
	v_mfma_f32_32x32x16_bf16 v[18:33], v[200:203], v[216:219], v[18:33]
	v_mfma_f32_32x32x16_bf16 v[34:49], v[208:211], v[212:215], v[34:49]
	s_waitcnt lgkmcnt(0)
	v_mfma_f32_32x32x16_bf16 v[18:33], v[208:211], v[220:223], v[18:33]
.LBB0_1071:
	s_min_u32 s14, s21, 25
	s_lshl_b32 s14, s14, 7
	v_lshl_add_u64 v[12:13], v[76:77], 0, s[14:15]
	s_waitcnt vmcnt(7)
	ds_write_b128 v80, v[58:61]
	s_waitcnt vmcnt(5)
	ds_write_b128 v80, v[66:69] offset:9216
	s_waitcnt lgkmcnt(0)
	s_barrier
	v_lshl_add_u64 v[14:15], v[78:79], 0, s[14:15]
	global_load_dwordx4 v[58:61], v[12:13], off offset:768
	global_load_dwordx4 v[66:69], v[14:15], off offset:768
	s_and_b64 vcc, exec, s[0:1]
	s_cbranch_vccnz .LBB0_1073
	ds_read_b128 v[12:15], v82
	ds_read_b128 v[84:87], v81 offset:9216
	ds_read_b128 v[88:91], v82 offset:32
	ds_read_b128 v[92:95], v81 offset:9248
	ds_read_b128 v[196:199], v81 offset:13824
	ds_read_b128 v[96:99], v81 offset:13856
	ds_read_b128 v[200:203], v82 offset:64
	ds_read_b128 v[204:207], v81 offset:9280
	ds_read_b128 v[208:211], v82 offset:96
	ds_read_b128 v[212:215], v81 offset:9312
	ds_read_b128 v[216:219], v81 offset:13888
	ds_read_b128 v[220:223], v81 offset:13920
	s_waitcnt lgkmcnt(10)
	v_mfma_f32_32x32x16_bf16 v[34:49], v[12:15], v[84:87], v[34:49]
	s_waitcnt lgkmcnt(7)
	v_mfma_f32_32x32x16_bf16 v[18:33], v[12:15], v[196:199], v[18:33]
	v_mfma_f32_32x32x16_bf16 v[34:49], v[88:91], v[92:95], v[34:49]
	s_waitcnt lgkmcnt(6)
	v_mfma_f32_32x32x16_bf16 v[18:33], v[88:91], v[96:99], v[18:33]
	s_waitcnt lgkmcnt(4)
	v_mfma_f32_32x32x16_bf16 v[34:49], v[200:203], v[204:207], v[34:49]
	s_waitcnt lgkmcnt(1)
	v_mfma_f32_32x32x16_bf16 v[18:33], v[200:203], v[216:219], v[18:33]
	v_mfma_f32_32x32x16_bf16 v[34:49], v[208:211], v[212:215], v[34:49]
	s_waitcnt lgkmcnt(0)
	v_mfma_f32_32x32x16_bf16 v[18:33], v[208:211], v[220:223], v[18:33]
.LBB0_1073:
	s_min_u32 s14, s21, 24
	s_lshl_b32 s14, s14, 7
	v_lshl_add_u64 v[12:13], v[76:77], 0, s[14:15]
	ds_write_b128 v80, v[62:65] offset:18432
	s_waitcnt vmcnt(6)
	ds_write_b128 v80, v[70:73] offset:27648
	s_waitcnt lgkmcnt(0)
	s_barrier
	v_lshl_add_u64 v[14:15], v[78:79], 0, s[14:15]
	global_load_dwordx4 v[62:65], v[12:13], off offset:896
	global_load_dwordx4 v[70:73], v[14:15], off offset:896
	s_and_b64 vcc, exec, s[0:1]
	s_cbranch_vccnz .LBB0_1066
	ds_read_b128 v[12:15], v82 offset:18432
	ds_read_b128 v[84:87], v81 offset:27648
	ds_read_b128 v[88:91], v82 offset:18464
	ds_read_b128 v[92:95], v81 offset:27680
	ds_read_b128 v[196:199], v81 offset:32256
	ds_read_b128 v[96:99], v81 offset:32288
	ds_read_b128 v[200:203], v82 offset:18496
	ds_read_b128 v[204:207], v81 offset:27712
	ds_read_b128 v[208:211], v82 offset:18528
	ds_read_b128 v[212:215], v81 offset:27744
	ds_read_b128 v[216:219], v81 offset:32320
	ds_read_b128 v[220:223], v81 offset:32352
	s_waitcnt lgkmcnt(10)
	v_mfma_f32_32x32x16_bf16 v[34:49], v[12:15], v[84:87], v[34:49]
	s_waitcnt lgkmcnt(7)
	v_mfma_f32_32x32x16_bf16 v[18:33], v[12:15], v[196:199], v[18:33]
	v_mfma_f32_32x32x16_bf16 v[34:49], v[88:91], v[92:95], v[34:49]
	s_waitcnt lgkmcnt(6)
	v_mfma_f32_32x32x16_bf16 v[18:33], v[88:91], v[96:99], v[18:33]
	s_waitcnt lgkmcnt(4)
	v_mfma_f32_32x32x16_bf16 v[34:49], v[200:203], v[204:207], v[34:49]
	s_waitcnt lgkmcnt(1)
	v_mfma_f32_32x32x16_bf16 v[18:33], v[200:203], v[216:219], v[18:33]
	v_mfma_f32_32x32x16_bf16 v[34:49], v[208:211], v[212:215], v[34:49]
	s_waitcnt lgkmcnt(0)
	v_mfma_f32_32x32x16_bf16 v[18:33], v[208:211], v[220:223], v[18:33]
	s_branch .LBB0_1066

; #define LAS __attribute__((address_space(3)))
; #define MFMA32(a, b, c) __builtin_amdgcn_mfma_f32_32x32x16_bf16((a), (b), (c), 0, 0, 0)
; #define GS_STEP(RF, RN, t) do { gs_load<ROWS>(RF, ap, bp, K, ((t) + 4 < nkt) ? (t) + 4 : nkt - 1); \
;         if (wave < ROWS / 32) gs_compute<ROWS>(acc0, acc1, lds + ((t) & 1) * BUF, wave, r, h2); \
;         gs_store<ROWS>(RN, lds + (((t) + 1) & 1) * BUF, soff); \
;         __syncthreads(); } while (0)
; template <int ROWS> DI void gs_load(GsRegs<ROWS>& R, const bf16* ap, const bf16* bp, int K, int kt) {
; #pragma unroll
;     for (int rep = 0; rep < ROWS / 64; ++rep) R.a[rep] = *(const u32x4*)(ap + (size_t)(64 * rep) * K + kt * 64);
;     R.b = *(const u32x4*)(bp + kt * 64);
; }
; template <int ROWS> DI void gs_store(const GsRegs<ROWS>& R, LAS unsigned char* buf, int soff) {
; #pragma unroll
;     for (int rep = 0; rep < ROWS / 64; ++rep) *(LAS u32x4*)(buf + soff + rep * (64 * GS_LD * 2)) = R.a[rep];
;     *(LAS u32x4*)(buf + ROWS * GS_LD * 2 + soff) = R.b;
; }
; template <int ROWS> DI void gs_compute(f32x16& acc0, f32x16& acc1, const LAS unsigned char* ab, int wave, int r, int h2) {
;     const LAS unsigned char* bb = ab + ROWS * GS_LD * 2;
; #pragma unroll
;     for (int s = 0; s < 4; ++s) {
;         const bf16x8 a = *(const LAS bf16x8*)(ab + ((32 * wave + r) * GS_LD + 16 * s + 8 * h2) * 2);
;         const bf16x8 b0 = *(const LAS bf16x8*)(bb + (r * GS_LD + 16 * s + 8 * h2) * 2), b1 = *(const LAS bf16x8*)(bb + ((32 + r) * GS_LD + 16 * s + 8 * h2) * 2);
;         acc0 = MFMA32(a, b0, acc0); acc1 = MFMA32(a, b1, acc1);
;     }
; }
; template <int ROWS, class Epi> DI void gemm_small_unit(LAS unsigned char* lds, const bf16* A, const bf16* Bt, int K, int m0, int n0, int n1, const Epi& E, int tid_, int wave) {
;     ...
; #pragma unroll 1
;     for (int kt = 0; kt < nkt; kt += 4) { GS_STEP(R0, R1, kt); GS_STEP(R1, R2, kt + 1); GS_STEP(R2, R3, kt + 2); GS_STEP(R3, R0, kt + 3); }
.LBB0_1422:
	s_cmp_gt_u32 s23, 11
	s_cselect_b64 s[16:17], -1, 0
	s_cmp_lt_u32 s23, 12
	s_cselect_b32 s12, s34, 0x3c0
	s_lshl_b64 s[0:1], s[12:13], 1
	v_lshl_add_u64 v[12:13], v[118:119], 0, s[0:1]
	v_add_co_u32_e32 v8, vcc, s19, v12
	v_cndmask_b32_e64 v2, 0, 1, s[10:11]
	s_nop 0
	v_addc_co_u32_e32 v9, vcc, 0, v13, vcc
	v_add_co_u32_e32 v14, vcc, 0x40000, v12
	global_load_dwordx4 v[4:7], v[12:13], off
	s_nop 0
	global_load_dwordx4 v[8:11], v[8:9], off
	v_addc_co_u32_e32 v15, vcc, 0, v13, vcc
	v_add_co_u32_e32 v16, vcc, 0x60000, v12
	s_nop 1
	v_addc_co_u32_e32 v17, vcc, 0, v13, vcc
	global_load_dwordx4 v[12:15], v[14:15], off
	s_nop 0
	global_load_dwordx4 v[110:113], v[16:17], off
	v_lshl_add_u64 v[16:17], v[120:121], 0, s[0:1]
	global_load_dwordx4 v[114:117], v[16:17], off
	v_cmp_ne_u32_e64 s[0:1], 1, v2
	s_andn2_b64 vcc, exec, s[10:11]
	s_cbranch_vccnz .LBB0_1424
	ds_read_b128 v[128:131], v127
	ds_read_b128 v[132:135], v125 offset:36864
	ds_read_b128 v[136:139], v127 offset:32
	ds_read_b128 v[140:143], v125 offset:36896
	ds_read_b128 v[196:199], v125 offset:41472
	ds_read_b128 v[144:147], v125 offset:41504
	ds_read_b128 v[200:203], v127 offset:64
	ds_read_b128 v[204:207], v125 offset:36928
	ds_read_b128 v[208:211], v127 offset:96
	ds_read_b128 v[212:215], v125 offset:36960
	ds_read_b128 v[216:219], v125 offset:41536
	ds_read_b128 v[220:223], v125 offset:41568
	s_waitcnt lgkmcnt(10)
	v_mfma_f32_32x32x16_bf16 v[18:33], v[128:131], v[132:135], v[18:33]
	s_waitcnt lgkmcnt(7)
	v_mfma_f32_32x32x16_bf16 v[34:49], v[128:131], v[196:199], v[34:49]
	v_mfma_f32_32x32x16_bf16 v[18:33], v[136:139], v[140:143], v[18:33]
	s_waitcnt lgkmcnt(6)
	v_mfma_f32_32x32x16_bf16 v[34:49], v[136:139], v[144:147], v[34:49]
	s_waitcnt lgkmcnt(4)
	v_mfma_f32_32x32x16_bf16 v[18:33], v[200:203], v[204:207], v[18:33]
	s_waitcnt lgkmcnt(1)
	v_mfma_f32_32x32x16_bf16 v[34:49], v[200:203], v[216:219], v[34:49]
	v_mfma_f32_32x32x16_bf16 v[18:33], v[208:211], v[212:215], v[18:33]
	s_waitcnt lgkmcnt(0)
	v_mfma_f32_32x32x16_bf16 v[34:49], v[208:211], v[220:223], v[34:49]
.LBB0_1424:
	s_min_u32 s12, s23, 10
	s_lshl_b32 s12, s12, 7
	s_waitcnt vmcnt(19)
	ds_write_b128 v124, v[50:53] offset:46080
	s_waitcnt vmcnt(18)
	ds_write_b128 v124, v[54:57] offset:55296
	s_waitcnt vmcnt(17)
	ds_write_b128 v124, v[66:69] offset:64512
	s_waitcnt vmcnt(16)
	ds_write_b128 v126, v[78:81] offset:27648
	v_lshl_add_u64 v[66:67], v[118:119], 0, s[12:13]
	v_add_co_u32_e32 v54, vcc, s19, v66
	v_add_u32_e32 v16, 0x14400, v124
	s_nop 0
	v_addc_co_u32_e32 v55, vcc, 0, v67, vcc
	v_add_co_u32_e32 v68, vcc, 0x40000, v66
	s_waitcnt vmcnt(15)
	ds_write_b128 v16, v[82:85]
	v_addc_co_u32_e32 v69, vcc, 0, v67, vcc
	v_add_co_u32_e32 v78, vcc, 0x60000, v66
	v_lshl_add_u64 v[82:83], v[120:121], 0, s[12:13]
	s_nop 0
	v_addc_co_u32_e32 v79, vcc, 0, v67, vcc
	s_waitcnt lgkmcnt(0)
	s_barrier
	global_load_dwordx4 v[50:53], v[66:67], off offset:640
	s_nop 0
	global_load_dwordx4 v[54:57], v[54:55], off offset:640
	s_nop 0
	global_load_dwordx4 v[66:69], v[68:69], off offset:640
	s_nop 0
	global_load_dwordx4 v[78:81], v[78:79], off offset:640
	s_and_b64 vcc, exec, s[0:1]
	global_load_dwordx4 v[82:85], v[82:83], off offset:640
	v_add_u32_e32 v2, 0x14400, v125
	s_cbranch_vccnz .LBB0_1426
	ds_read_b128 v[128:131], v127 offset:46080
	ds_read_b128 v[132:135], v2
	ds_read_b128 v[136:139], v127 offset:46112
	ds_read_b128 v[140:143], v2 offset:32
	ds_read_b128 v[196:199], v2 offset:4608
	ds_read_b128 v[144:147], v2 offset:4640
	ds_read_b128 v[200:203], v127 offset:46144
	ds_read_b128 v[204:207], v2 offset:64
	ds_read_b128 v[208:211], v127 offset:46176
	ds_read_b128 v[212:215], v2 offset:96
	ds_read_b128 v[216:219], v2 offset:4672
	ds_read_b128 v[220:223], v2 offset:4704
	s_waitcnt lgkmcnt(10)
	v_mfma_f32_32x32x16_bf16 v[18:33], v[128:131], v[132:135], v[18:33]
	s_waitcnt lgkmcnt(7)
	v_mfma_f32_32x32x16_bf16 v[34:49], v[128:131], v[196:199], v[34:49]
	v_mfma_f32_32x32x16_bf16 v[18:33], v[136:139], v[140:143], v[18:33]
	s_waitcnt lgkmcnt(6)
	v_mfma_f32_32x32x16_bf16 v[34:49], v[136:139], v[144:147], v[34:49]
	s_waitcnt lgkmcnt(4)
	v_mfma_f32_32x32x16_bf16 v[18:33], v[200:203], v[204:207], v[18:33]
	s_waitcnt lgkmcnt(1)
	v_mfma_f32_32x32x16_bf16 v[34:49], v[200:203], v[216:219], v[34:49]
	v_mfma_f32_32x32x16_bf16 v[18:33], v[208:211], v[212:215], v[18:33]
	s_waitcnt lgkmcnt(0)
	v_mfma_f32_32x32x16_bf16 v[34:49], v[208:211], v[220:223], v[34:49]
; #define LAS __attribute__((address_space(3)))
; #define MFMA32(a, b, c) __builtin_amdgcn_mfma_f32_32x32x16_bf16((a), (b), (c), 0, 0, 0)
; #define GS_STEP(RF, RN, t) do { gs_load<ROWS>(RF, ap, bp, K, ((t) + 4 < nkt) ? (t) + 4 : nkt - 1); \
;         if (wave < ROWS / 32) gs_compute<ROWS>(acc0, acc1, lds + ((t) & 1) * BUF, wave, r, h2); \
;         gs_store<ROWS>(RN, lds + (((t) + 1) & 1) * BUF, soff); \
;         __syncthreads(); } while (0)
; template <int ROWS> DI void gs_load(GsRegs<ROWS>& R, const bf16* ap, const bf16* bp, int K, int kt) {
; #pragma unroll
;     for (int rep = 0; rep < ROWS / 64; ++rep) R.a[rep] = *(const u32x4*)(ap + (size_t)(64 * rep) * K + kt * 64);
;     R.b = *(const u32x4*)(bp + kt * 64);
; }
; template <int ROWS> DI void gs_store(const GsRegs<ROWS>& R, LAS unsigned char* buf, int soff) {
; #pragma unroll
;     for (int rep = 0; rep < ROWS / 64; ++rep) *(LAS u32x4*)(buf + soff + rep * (64 * GS_LD * 2)) = R.a[rep];
;     *(LAS u32x4*)(buf + ROWS * GS_LD * 2 + soff) = R.b;
; }
; template <int ROWS> DI void gs_compute(f32x16& acc0, f32x16& acc1, const LAS unsigned char* ab, int wave, int r, int h2) {
;     const LAS unsigned char* bb = ab + ROWS * GS_LD * 2;
; #pragma unroll
;     for (int s = 0; s < 4; ++s) {
;         const bf16x8 a = *(const LAS bf16x8*)(ab + ((32 * wave + r) * GS_LD + 16 * s + 8 * h2) * 2);
;         const bf16x8 b0 = *(const LAS bf16x8*)(bb + (r * GS_LD + 16 * s + 8 * h2) * 2), b1 = *(const LAS bf16x8*)(bb + ((32 + r) * GS_LD + 16 * s + 8 * h2) * 2);
;         acc0 = MFMA32(a, b0, acc0); acc1 = MFMA32(a, b1, acc1);
;     }
; }
; template <int ROWS, class Epi> DI void gemm_small_unit(LAS unsigned char* lds, const bf16* A, const bf16* Bt, int K, int m0, int n0, int n1, const Epi& E, int tid_, int wave) {
;     ...
; #pragma unroll 1
;     for (int kt = 0; kt < nkt; kt += 4) { GS_STEP(R0, R1, kt); GS_STEP(R1, R2, kt + 1); GS_STEP(R2, R3, kt + 2); GS_STEP(R3, R0, kt + 3); }
.LBB0_1426:
	s_min_u32 s12, s23, 9
	s_lshl_b32 s12, s12, 7
	s_waitcnt vmcnt(19)
	ds_write_b128 v124, v[58:61]
	s_waitcnt vmcnt(17)
	ds_write_b128 v124, v[70:73] offset:9216
	s_waitcnt vmcnt(15)
	ds_write_b128 v124, v[86:89] offset:18432
	s_waitcnt vmcnt(11)
	ds_write_b128 v124, v[102:105] offset:27648
	ds_write_b128 v124, v[94:97] offset:36864
	v_lshl_add_u64 v[86:87], v[118:119], 0, s[12:13]
	v_add_co_u32_e32 v70, vcc, 0x20000, v86
	s_waitcnt lgkmcnt(0)
	s_nop 0
	v_addc_co_u32_e32 v71, vcc, 0, v87, vcc
	v_add_co_u32_e32 v88, vcc, 0x40000, v86
	s_barrier
	s_nop 0
	v_addc_co_u32_e32 v89, vcc, 0, v87, vcc
	v_add_co_u32_e32 v94, vcc, 0x60000, v86
	s_nop 1
	v_addc_co_u32_e32 v95, vcc, 0, v87, vcc
	global_load_dwordx4 v[58:61], v[86:87], off offset:768
	s_nop 0
	global_load_dwordx4 v[70:73], v[70:71], off offset:768
	s_nop 0
	global_load_dwordx4 v[86:89], v[88:89], off offset:768
	s_nop 0
	global_load_dwordx4 v[102:105], v[94:95], off offset:768
	v_lshl_add_u64 v[94:95], v[120:121], 0, s[12:13]
	global_load_dwordx4 v[94:97], v[94:95], off offset:768
	s_and_b64 vcc, exec, s[0:1]
	s_cbranch_vccnz .LBB0_1428
	ds_read_b128 v[128:131], v127
	ds_read_b128 v[132:135], v125 offset:36864
	ds_read_b128 v[136:139], v127 offset:32
	ds_read_b128 v[140:143], v125 offset:36896
	ds_read_b128 v[196:199], v125 offset:41472
	ds_read_b128 v[144:147], v125 offset:41504
	ds_read_b128 v[200:203], v127 offset:64
	ds_read_b128 v[204:207], v125 offset:36928
	ds_read_b128 v[208:211], v127 offset:96
	ds_read_b128 v[212:215], v125 offset:36960
	ds_read_b128 v[216:219], v125 offset:41536
	ds_read_b128 v[220:223], v125 offset:41568
	s_waitcnt lgkmcnt(10)
	v_mfma_f32_32x32x16_bf16 v[18:33], v[128:131], v[132:135], v[18:33]
	s_waitcnt lgkmcnt(7)
	v_mfma_f32_32x32x16_bf16 v[34:49], v[128:131], v[196:199], v[34:49]
	v_mfma_f32_32x32x16_bf16 v[18:33], v[136:139], v[140:143], v[18:33]
	s_waitcnt lgkmcnt(6)
	v_mfma_f32_32x32x16_bf16 v[34:49], v[136:139], v[144:147], v[34:49]
	s_waitcnt lgkmcnt(4)
	v_mfma_f32_32x32x16_bf16 v[18:33], v[200:203], v[204:207], v[18:33]
	s_waitcnt lgkmcnt(1)
	v_mfma_f32_32x32x16_bf16 v[34:49], v[200:203], v[216:219], v[34:49]
	v_mfma_f32_32x32x16_bf16 v[18:33], v[208:211], v[212:215], v[18:33]
	s_waitcnt lgkmcnt(0)
	v_mfma_f32_32x32x16_bf16 v[34:49], v[208:211], v[220:223], v[34:49]
.LBB0_1428:
	s_min_u32 s12, s23, 8
	s_lshl_b32 s12, s12, 7
	ds_write_b128 v124, v[62:65] offset:46080
	ds_write_b128 v124, v[74:77] offset:55296
	ds_write_b128 v124, v[90:93] offset:64512
	s_waitcnt vmcnt(15)
	ds_write_b128 v126, v[106:109] offset:27648
	ds_write_b128 v16, v[98:101]
	v_lshl_add_u64 v[16:17], v[118:119], 0, s[12:13]
	v_add_co_u32_e32 v74, vcc, 0x20000, v16
	s_waitcnt lgkmcnt(0)
	s_nop 0
	v_addc_co_u32_e32 v75, vcc, 0, v17, vcc
	v_add_co_u32_e32 v90, vcc, 0x40000, v16
	s_barrier
	s_nop 0
	v_addc_co_u32_e32 v91, vcc, 0, v17, vcc
	global_load_dwordx4 v[62:65], v[16:17], off offset:896
	s_nop 0
	global_load_dwordx4 v[74:77], v[74:75], off offset:896
	v_add_co_u32_e32 v16, vcc, 0x60000, v16
	s_nop 1
	v_addc_co_u32_e32 v17, vcc, 0, v17, vcc
	global_load_dwordx4 v[90:93], v[90:91], off offset:896
	s_nop 0
	global_load_dwordx4 v[106:109], v[16:17], off offset:896
	v_lshl_add_u64 v[16:17], v[120:121], 0, s[12:13]
	global_load_dwordx4 v[98:101], v[16:17], off offset:896
	s_and_b64 vcc, exec, s[0:1]
	s_cbranch_vccnz .LBB0_1421
	ds_read_b128 v[128:131], v127 offset:46080
	ds_read_b128 v[132:135], v2
	ds_read_b128 v[136:139], v127 offset:46112
	ds_read_b128 v[140:143], v2 offset:32
	ds_read_b128 v[196:199], v2 offset:4608
	ds_read_b128 v[144:147], v2 offset:4640
	ds_read_b128 v[200:203], v127 offset:46144
	ds_read_b128 v[204:207], v2 offset:64
	ds_read_b128 v[208:211], v127 offset:46176
	ds_read_b128 v[212:215], v2 offset:96
	ds_read_b128 v[216:219], v2 offset:4672
	ds_read_b128 v[220:223], v2 offset:4704
	s_waitcnt lgkmcnt(10)
	v_mfma_f32_32x32x16_bf16 v[18:33], v[128:131], v[132:135], v[18:33]
	s_waitcnt lgkmcnt(7)
	v_mfma_f32_32x32x16_bf16 v[34:49], v[128:131], v[196:199], v[34:49]
	v_mfma_f32_32x32x16_bf16 v[18:33], v[136:139], v[140:143], v[18:33]
	s_waitcnt lgkmcnt(6)
	v_mfma_f32_32x32x16_bf16 v[34:49], v[136:139], v[144:147], v[34:49]
	s_waitcnt lgkmcnt(4)
	v_mfma_f32_32x32x16_bf16 v[18:33], v[200:203], v[204:207], v[18:33]
	s_waitcnt lgkmcnt(1)
	v_mfma_f32_32x32x16_bf16 v[34:49], v[200:203], v[216:219], v[34:49]
	v_mfma_f32_32x32x16_bf16 v[18:33], v[208:211], v[212:215], v[18:33]
	s_waitcnt lgkmcnt(0)
	v_mfma_f32_32x32x16_bf16 v[34:49], v[208:211], v[220:223], v[34:49]
	s_branch .LBB0_1421

; #define LAS __attribute__((address_space(3)))
; #define MFMA32(a, b, c) __builtin_amdgcn_mfma_f32_32x32x16_bf16((a), (b), (c), 0, 0, 0)
; #define GS_STEP(RF, RN, t) do { gs_load<ROWS>(RF, ap, bp, K, ((t) + 4 < nkt) ? (t) + 4 : nkt - 1); \
;         if (wave < ROWS / 32) gs_compute<ROWS>(acc0, acc1, lds + ((t) & 1) * BUF, wave, r, h2); \
;         gs_store<ROWS>(RN, lds + (((t) + 1) & 1) * BUF, soff); \
;         __syncthreads(); } while (0)
; template <int ROWS> DI void gs_load(GsRegs<ROWS>& R, const bf16* ap, const bf16* bp, int K, int kt) {
; #pragma unroll
;     for (int rep = 0; rep < ROWS / 64; ++rep) R.a[rep] = *(const u32x4*)(ap + (size_t)(64 * rep) * K + kt * 64);
;     R.b = *(const u32x4*)(bp + kt * 64);
; }
; template <int ROWS> DI void gs_store(const GsRegs<ROWS>& R, LAS unsigned char* buf, int soff) {
; #pragma unroll
;     for (int rep = 0; rep < ROWS / 64; ++rep) *(LAS u32x4*)(buf + soff + rep * (64 * GS_LD * 2)) = R.a[rep];
;     *(LAS u32x4*)(buf + ROWS * GS_LD * 2 + soff) = R.b;
; }
; template <int ROWS> DI void gs_compute(f32x16& acc0, f32x16& acc1, const LAS unsigned char* ab, int wave, int r, int h2) {
;     const LAS unsigned char* bb = ab + ROWS * GS_LD * 2;
; #pragma unroll
;     for (int s = 0; s < 4; ++s) {
;         const bf16x8 a = *(const LAS bf16x8*)(ab + ((32 * wave + r) * GS_LD + 16 * s + 8 * h2) * 2);
;         const bf16x8 b0 = *(const LAS bf16x8*)(bb + (r * GS_LD + 16 * s + 8 * h2) * 2), b1 = *(const LAS bf16x8*)(bb + ((32 + r) * GS_LD + 16 * s + 8 * h2) * 2);
;         acc0 = MFMA32(a, b0, acc0); acc1 = MFMA32(a, b1, acc1);
;     }
; }
; template <int ROWS, class Epi> DI void gemm_small_unit(LAS unsigned char* lds, const bf16* A, const bf16* Bt, int K, int m0, int n0, int n1, const Epi& E, int tid_, int wave) {
;     ...
; #pragma unroll 1
;     for (int kt = 0; kt < nkt; kt += 4) { GS_STEP(R0, R1, kt); GS_STEP(R1, R2, kt + 1); GS_STEP(R2, R3, kt + 2); GS_STEP(R3, R0, kt + 3); }
.LBB0_1977:
	s_cmp_gt_u32 s21, 11
	s_cselect_b64 s[16:17], -1, 0
	s_cmp_lt_u32 s21, 12
	s_cselect_b32 s14, s20, 0x3c0
	s_lshl_b64 s[22:23], s[14:15], 1
	v_lshl_add_u64 v[12:13], v[76:77], 0, s[22:23]
	v_lshl_add_u64 v[14:15], v[78:79], 0, s[22:23]
	global_load_dwordx4 v[4:7], v[12:13], off
	global_load_dwordx4 v[8:11], v[14:15], off
	s_and_b64 vcc, exec, s[0:1]
	s_cbranch_vccnz .LBB0_1979
	ds_read_b128 v[12:15], v82
	ds_read_b128 v[84:87], v81 offset:9216
	ds_read_b128 v[88:91], v82 offset:32
	ds_read_b128 v[92:95], v81 offset:9248
	ds_read_b128 v[196:199], v81 offset:13824
	ds_read_b128 v[96:99], v81 offset:13856
	ds_read_b128 v[200:203], v82 offset:64
	ds_read_b128 v[204:207], v81 offset:9280
	ds_read_b128 v[208:211], v82 offset:96
	ds_read_b128 v[212:215], v81 offset:9312
	ds_read_b128 v[216:219], v81 offset:13888
	ds_read_b128 v[220:223], v81 offset:13920
	s_waitcnt lgkmcnt(10)
	v_mfma_f32_32x32x16_bf16 v[34:49], v[12:15], v[84:87], v[34:49]
	s_waitcnt lgkmcnt(7)
	v_mfma_f32_32x32x16_bf16 v[18:33], v[12:15], v[196:199], v[18:33]
	v_mfma_f32_32x32x16_bf16 v[34:49], v[88:91], v[92:95], v[34:49]
	s_waitcnt lgkmcnt(6)
	v_mfma_f32_32x32x16_bf16 v[18:33], v[88:91], v[96:99], v[18:33]
	s_waitcnt lgkmcnt(4)
	v_mfma_f32_32x32x16_bf16 v[34:49], v[200:203], v[204:207], v[34:49]
	s_waitcnt lgkmcnt(1)
	v_mfma_f32_32x32x16_bf16 v[18:33], v[200:203], v[216:219], v[18:33]
	v_mfma_f32_32x32x16_bf16 v[34:49], v[208:211], v[212:215], v[34:49]
	s_waitcnt lgkmcnt(0)
	v_mfma_f32_32x32x16_bf16 v[18:33], v[208:211], v[220:223], v[18:33]

; #define LAS __attribute__((address_space(3)))
; #define MFMA32(a, b, c) __builtin_amdgcn_mfma_f32_32x32x16_bf16((a), (b), (c), 0, 0, 0)
; #define GS_STEP(RF, RN, t) do { gs_load<ROWS>(RF, ap, bp, K, ((t) + 4 < nkt) ? (t) + 4 : nkt - 1); \
;         if (wave < ROWS / 32) gs_compute<ROWS>(acc0, acc1, lds + ((t) & 1) * BUF, wave, r, h2); \
;         gs_store<ROWS>(RN, lds + (((t) + 1) & 1) * BUF, soff); \
;         __syncthreads(); } while (0)
; template <int ROWS> DI void gs_load(GsRegs<ROWS>& R, const bf16* ap, const bf16* bp, int K, int kt) {
; #pragma unroll
;     for (int rep = 0; rep < ROWS / 64; ++rep) R.a[rep] = *(const u32x4*)(ap + (size_t)(64 * rep) * K + kt * 64);
;     R.b = *(const u32x4*)(bp + kt * 64);
; }
; template <int ROWS> DI void gs_store(const GsRegs<ROWS>& R, LAS unsigned char* buf, int soff) {
; #pragma unroll
;     for (int rep = 0; rep < ROWS / 64; ++rep) *(LAS u32x4*)(buf + soff + rep * (64 * GS_LD * 2)) = R.a[rep];
;     *(LAS u32x4*)(buf + ROWS * GS_LD * 2 + soff) = R.b;
; }
; template <int ROWS> DI void gs_compute(f32x16& acc0, f32x16& acc1, const LAS unsigned char* ab, int wave, int r, int h2) {
;     const LAS unsigned char* bb = ab + ROWS * GS_LD * 2;
; #pragma unroll
;     for (int s = 0; s < 4; ++s) {
;         const bf16x8 a = *(const LAS bf16x8*)(ab + ((32 * wave + r) * GS_LD + 16 * s + 8 * h2) * 2);
;         const bf16x8 b0 = *(const LAS bf16x8*)(bb + (r * GS_LD + 16 * s + 8 * h2) * 2), b1 = *(const LAS bf16x8*)(bb + ((32 + r) * GS_LD + 16 * s + 8 * h2) * 2);
;         acc0 = MFMA32(a, b0, acc0); acc1 = MFMA32(a, b1, acc1);
;     }
; }
; template <int ROWS, class Epi> DI void gemm_small_unit(LAS unsigned char* lds, const bf16* A, const bf16* Bt, int K, int m0, int n0, int n1, const Epi& E, int tid_, int wave) {
;     ...
; #pragma unroll 1
;     for (int kt = 0; kt < nkt; kt += 4) { GS_STEP(R0, R1, kt); GS_STEP(R1, R2, kt + 1); GS_STEP(R2, R3, kt + 2); GS_STEP(R3, R0, kt + 3); }
.LBB0_2098:
	s_cmp_gt_u32 s21, 11
	s_cselect_b64 s[14:15], -1, 0
	s_cmp_lt_u32 s21, 12
	s_cselect_b32 s12, s20, 0x3c0
	s_lshl_b64 s[0:1], s[12:13], 1
	v_lshl_add_u64 v[80:81], v[84:85], 0, s[0:1]
	v_add_co_u32_e32 v82, vcc, 0x20000, v80
	v_cndmask_b32_e64 v2, 0, 1, s[10:11]
	s_nop 0
	v_addc_co_u32_e32 v83, vcc, 0, v81, vcc
	global_load_dwordx4 v[72:75], v[80:81], off
	global_load_dwordx4 v[76:79], v[82:83], off
	v_lshl_add_u64 v[80:81], v[86:87], 0, s[0:1]
	global_load_dwordx4 v[80:83], v[80:81], off
	v_cmp_ne_u32_e64 s[0:1], 1, v2
	s_andn2_b64 vcc, exec, s[10:11]
	s_cbranch_vccnz .LBB0_2100
	ds_read_b128 v[94:97], v92
	ds_read_b128 v[98:101], v91 offset:18432
	ds_read_b128 v[102:105], v92 offset:32
	ds_read_b128 v[106:109], v91 offset:18464
	ds_read_b128 v[196:199], v91 offset:23040
	ds_read_b128 v[110:113], v91 offset:23072
	ds_read_b128 v[200:203], v92 offset:64
	ds_read_b128 v[204:207], v91 offset:18496
	ds_read_b128 v[208:211], v92 offset:96
	ds_read_b128 v[212:215], v91 offset:18528
	ds_read_b128 v[216:219], v91 offset:23104
	ds_read_b128 v[220:223], v91 offset:23136
	s_waitcnt lgkmcnt(10)
	v_mfma_f32_32x32x16_bf16 v[20:35], v[94:97], v[98:101], v[20:35]
	s_waitcnt lgkmcnt(7)
	v_mfma_f32_32x32x16_bf16 v[4:19], v[94:97], v[196:199], v[4:19]
	v_mfma_f32_32x32x16_bf16 v[20:35], v[102:105], v[106:109], v[20:35]
	s_waitcnt lgkmcnt(6)
	v_mfma_f32_32x32x16_bf16 v[4:19], v[102:105], v[110:113], v[4:19]
	s_waitcnt lgkmcnt(4)
	v_mfma_f32_32x32x16_bf16 v[20:35], v[200:203], v[204:207], v[20:35]
	s_waitcnt lgkmcnt(1)
	v_mfma_f32_32x32x16_bf16 v[4:19], v[200:203], v[216:219], v[4:19]
	v_mfma_f32_32x32x16_bf16 v[20:35], v[208:211], v[212:215], v[20:35]
	s_waitcnt lgkmcnt(0)
	v_mfma_f32_32x32x16_bf16 v[4:19], v[208:211], v[220:223], v[4:19]
.LBB0_2100:
	s_min_u32 s12, s21, 10
	s_lshl_b32 s12, s12, 7
	s_waitcnt vmcnt(11)
	ds_write_b128 v90, v[36:39] offset:27648
	s_waitcnt vmcnt(10)
	ds_write_b128 v90, v[40:43] offset:36864
	s_waitcnt vmcnt(9)
	ds_write_b128 v90, v[52:55] offset:46080
	v_lshl_add_u64 v[52:53], v[84:85], 0, s[12:13]
	v_add_co_u32_e32 v54, vcc, 0x20000, v52
	s_waitcnt lgkmcnt(0)
	s_barrier
	v_addc_co_u32_e32 v55, vcc, 0, v53, vcc
	global_load_dwordx4 v[36:39], v[52:53], off offset:640
	global_load_dwordx4 v[40:43], v[54:55], off offset:640
	v_lshl_add_u64 v[52:53], v[86:87], 0, s[12:13]
	global_load_dwordx4 v[52:55], v[52:53], off offset:640
	s_and_b64 vcc, exec, s[0:1]
	s_cbranch_vccnz .LBB0_2102
	ds_read_b128 v[94:97], v92 offset:27648
	ds_read_b128 v[98:101], v91 offset:46080
	ds_read_b128 v[102:105], v92 offset:27680
	ds_read_b128 v[106:109], v91 offset:46112
	ds_read_b128 v[196:199], v91 offset:50688
	ds_read_b128 v[110:113], v91 offset:50720
	ds_read_b128 v[200:203], v92 offset:27712
	ds_read_b128 v[204:207], v91 offset:46144
	ds_read_b128 v[208:211], v92 offset:27744
	ds_read_b128 v[212:215], v91 offset:46176
	ds_read_b128 v[216:219], v91 offset:50752
	ds_read_b128 v[220:223], v91 offset:50784
	s_waitcnt lgkmcnt(10)
	v_mfma_f32_32x32x16_bf16 v[20:35], v[94:97], v[98:101], v[20:35]
	s_waitcnt lgkmcnt(7)
	v_mfma_f32_32x32x16_bf16 v[4:19], v[94:97], v[196:199], v[4:19]
	v_mfma_f32_32x32x16_bf16 v[20:35], v[102:105], v[106:109], v[20:35]
	s_waitcnt lgkmcnt(6)
	v_mfma_f32_32x32x16_bf16 v[4:19], v[102:105], v[110:113], v[4:19]
	s_waitcnt lgkmcnt(4)
	v_mfma_f32_32x32x16_bf16 v[20:35], v[200:203], v[204:207], v[20:35]
	s_waitcnt lgkmcnt(1)
	v_mfma_f32_32x32x16_bf16 v[4:19], v[200:203], v[216:219], v[4:19]
	v_mfma_f32_32x32x16_bf16 v[20:35], v[208:211], v[212:215], v[20:35]
	s_waitcnt lgkmcnt(0)
	v_mfma_f32_32x32x16_bf16 v[4:19], v[208:211], v[220:223], v[4:19]
; #define LAS __attribute__((address_space(3)))
; #define MFMA32(a, b, c) __builtin_amdgcn_mfma_f32_32x32x16_bf16((a), (b), (c), 0, 0, 0)
; #define GS_STEP(RF, RN, t) do { gs_load<ROWS>(RF, ap, bp, K, ((t) + 4 < nkt) ? (t) + 4 : nkt - 1); \
;         if (wave < ROWS / 32) gs_compute<ROWS>(acc0, acc1, lds + ((t) & 1) * BUF, wave, r, h2); \
;         gs_store<ROWS>(RN, lds + (((t) + 1) & 1) * BUF, soff); \
;         __syncthreads(); } while (0)
; template <int ROWS> DI void gs_load(GsRegs<ROWS>& R, const bf16* ap, const bf16* bp, int K, int kt) {
; #pragma unroll
;     for (int rep = 0; rep < ROWS / 64; ++rep) R.a[rep] = *(const u32x4*)(ap + (size_t)(64 * rep) * K + kt * 64);
;     R.b = *(const u32x4*)(bp + kt * 64);
; }
; template <int ROWS> DI void gs_store(const GsRegs<ROWS>& R, LAS unsigned char* buf, int soff) {
; #pragma unroll
;     for (int rep = 0; rep < ROWS / 64; ++rep) *(LAS u32x4*)(buf + soff + rep * (64 * GS_LD * 2)) = R.a[rep];
;     *(LAS u32x4*)(buf + ROWS * GS_LD * 2 + soff) = R.b;
; }
; template <int ROWS> DI void gs_compute(f32x16& acc0, f32x16& acc1, const LAS unsigned char* ab, int wave, int r, int h2) {
;     const LAS unsigned char* bb = ab + ROWS * GS_LD * 2;
; #pragma unroll
;     for (int s = 0; s < 4; ++s) {
;         const bf16x8 a = *(const LAS bf16x8*)(ab + ((32 * wave + r) * GS_LD + 16 * s + 8 * h2) * 2);
;         const bf16x8 b0 = *(const LAS bf16x8*)(bb + (r * GS_LD + 16 * s + 8 * h2) * 2), b1 = *(const LAS bf16x8*)(bb + ((32 + r) * GS_LD + 16 * s + 8 * h2) * 2);
;         acc0 = MFMA32(a, b0, acc0); acc1 = MFMA32(a, b1, acc1);
;     }
; }
; template <int ROWS, class Epi> DI void gemm_small_unit(LAS unsigned char* lds, const bf16* A, const bf16* Bt, int K, int m0, int n0, int n1, const Epi& E, int tid_, int wave) {
;     ...
; #pragma unroll 1
;     for (int kt = 0; kt < nkt; kt += 4) { GS_STEP(R0, R1, kt); GS_STEP(R1, R2, kt + 1); GS_STEP(R2, R3, kt + 2); GS_STEP(R3, R0, kt + 3); }
.LBB0_2102:
	s_min_u32 s12, s21, 9
	s_lshl_b32 s12, s12, 7
	s_waitcnt vmcnt(11)
	ds_write_b128 v90, v[44:47]
	s_waitcnt vmcnt(9)
	ds_write_b128 v90, v[56:59] offset:9216
	s_waitcnt vmcnt(7)
	ds_write_b128 v90, v[64:67] offset:18432
	v_lshl_add_u64 v[64:65], v[84:85], 0, s[12:13]
	v_add_co_u32_e32 v66, vcc, 0x20000, v64
	s_waitcnt lgkmcnt(0)
	s_barrier
	v_addc_co_u32_e32 v67, vcc, 0, v65, vcc
	global_load_dwordx4 v[44:47], v[64:65], off offset:768
	global_load_dwordx4 v[56:59], v[66:67], off offset:768
	v_lshl_add_u64 v[64:65], v[86:87], 0, s[12:13]
	global_load_dwordx4 v[64:67], v[64:65], off offset:768
	s_and_b64 vcc, exec, s[0:1]
	s_cbranch_vccnz .LBB0_2104
	ds_read_b128 v[94:97], v92
	ds_read_b128 v[98:101], v91 offset:18432
	ds_read_b128 v[102:105], v92 offset:32
	ds_read_b128 v[106:109], v91 offset:18464
	ds_read_b128 v[196:199], v91 offset:23040
	ds_read_b128 v[110:113], v91 offset:23072
	ds_read_b128 v[200:203], v92 offset:64
	ds_read_b128 v[204:207], v91 offset:18496
	ds_read_b128 v[208:211], v92 offset:96
	ds_read_b128 v[212:215], v91 offset:18528
	ds_read_b128 v[216:219], v91 offset:23104
	ds_read_b128 v[220:223], v91 offset:23136
	s_waitcnt lgkmcnt(10)
	v_mfma_f32_32x32x16_bf16 v[20:35], v[94:97], v[98:101], v[20:35]
	s_waitcnt lgkmcnt(7)
	v_mfma_f32_32x32x16_bf16 v[4:19], v[94:97], v[196:199], v[4:19]
	v_mfma_f32_32x32x16_bf16 v[20:35], v[102:105], v[106:109], v[20:35]
	s_waitcnt lgkmcnt(6)
	v_mfma_f32_32x32x16_bf16 v[4:19], v[102:105], v[110:113], v[4:19]
	s_waitcnt lgkmcnt(4)
	v_mfma_f32_32x32x16_bf16 v[20:35], v[200:203], v[204:207], v[20:35]
	s_waitcnt lgkmcnt(1)
	v_mfma_f32_32x32x16_bf16 v[4:19], v[200:203], v[216:219], v[4:19]
	v_mfma_f32_32x32x16_bf16 v[20:35], v[208:211], v[212:215], v[20:35]
	s_waitcnt lgkmcnt(0)
	v_mfma_f32_32x32x16_bf16 v[4:19], v[208:211], v[220:223], v[4:19]
.LBB0_2104:
	s_min_u32 s12, s21, 8
	s_lshl_b32 s12, s12, 7
	ds_write_b128 v90, v[48:51] offset:27648
	ds_write_b128 v90, v[60:63] offset:36864
	s_waitcnt vmcnt(9)
	ds_write_b128 v90, v[68:71] offset:46080
	v_lshl_add_u64 v[68:69], v[84:85], 0, s[12:13]
	v_add_co_u32_e32 v70, vcc, 0x20000, v68
	s_waitcnt lgkmcnt(0)
	s_barrier
	v_addc_co_u32_e32 v71, vcc, 0, v69, vcc
	global_load_dwordx4 v[48:51], v[68:69], off offset:896
	global_load_dwordx4 v[60:63], v[70:71], off offset:896
	v_lshl_add_u64 v[68:69], v[86:87], 0, s[12:13]
	global_load_dwordx4 v[68:71], v[68:69], off offset:896
	s_and_b64 vcc, exec, s[0:1]
	s_cbranch_vccnz .LBB0_2097
	ds_read_b128 v[94:97], v92 offset:27648
	ds_read_b128 v[98:101], v91 offset:46080
	ds_read_b128 v[102:105], v92 offset:27680
	ds_read_b128 v[106:109], v91 offset:46112
	ds_read_b128 v[196:199], v91 offset:50688
	ds_read_b128 v[110:113], v91 offset:50720
	ds_read_b128 v[200:203], v92 offset:27712
	ds_read_b128 v[204:207], v91 offset:46144
	ds_read_b128 v[208:211], v92 offset:27744
	ds_read_b128 v[212:215], v91 offset:46176
	ds_read_b128 v[216:219], v91 offset:50752
	ds_read_b128 v[220:223], v91 offset:50784
	s_waitcnt lgkmcnt(10)
	v_mfma_f32_32x32x16_bf16 v[20:35], v[94:97], v[98:101], v[20:35]
	s_waitcnt lgkmcnt(7)
	v_mfma_f32_32x32x16_bf16 v[4:19], v[94:97], v[196:199], v[4:19]
	v_mfma_f32_32x32x16_bf16 v[20:35], v[102:105], v[106:109], v[20:35]
	s_waitcnt lgkmcnt(6)
	v_mfma_f32_32x32x16_bf16 v[4:19], v[102:105], v[110:113], v[4:19]
	s_waitcnt lgkmcnt(4)
	v_mfma_f32_32x32x16_bf16 v[20:35], v[200:203], v[204:207], v[20:35]
	s_waitcnt lgkmcnt(1)
	v_mfma_f32_32x32x16_bf16 v[4:19], v[200:203], v[216:219], v[4:19]
	v_mfma_f32_32x32x16_bf16 v[20:35], v[208:211], v[212:215], v[20:35]
	s_waitcnt lgkmcnt(0)
	v_mfma_f32_32x32x16_bf16 v[4:19], v[208:211], v[220:223], v[4:19]
	s_branch .LBB0_2097

; #define LAS __attribute__((address_space(3)))
; #define MFMA32(a, b, c) __builtin_amdgcn_mfma_f32_32x32x16_bf16((a), (b), (c), 0, 0, 0)
; #define GS_STEP(RF, RN, t) do { gs_load<ROWS>(RF, ap, bp, K, ((t) + 4 < nkt) ? (t) + 4 : nkt - 1); \
;         if (wave < ROWS / 32) gs_compute<ROWS>(acc0, acc1, lds + ((t) & 1) * BUF, wave, r, h2); \
;         gs_store<ROWS>(RN, lds + (((t) + 1) & 1) * BUF, soff); \
;         __syncthreads(); } while (0)
; template <int ROWS> DI void gs_compute(f32x16& acc0, f32x16& acc1, const LAS unsigned char* ab, int wave, int r, int h2) {
;     const LAS unsigned char* bb = ab + ROWS * GS_LD * 2;
; #pragma unroll
;     for (int s = 0; s < 4; ++s) {
;         const bf16x8 a = *(const LAS bf16x8*)(ab + ((32 * wave + r) * GS_LD + 16 * s + 8 * h2) * 2);
;         const bf16x8 b0 = *(const LAS bf16x8*)(bb + (r * GS_LD + 16 * s + 8 * h2) * 2), b1 = *(const LAS bf16x8*)(bb + ((32 + r) * GS_LD + 16 * s + 8 * h2) * 2);
;         acc0 = MFMA32(a, b0, acc0); acc1 = MFMA32(a, b1, acc1);
;     }
; }
; template <int ROWS, class Epi> DI void gemm_small_unit(LAS unsigned char* lds, const bf16* A, const bf16* Bt, int K, int m0, int n0, int n1, const Epi& E, int tid_, int wave) {
;     constexpr int BUF = (ROWS + 64) * GS_LD * 2;
;     int tid = tid_; asm volatile("" : "+v"(tid));
;     const int lane = tid & 63, r = lane & 31, h2 = lane >> 5;
;     const int arow = tid >> 3, ck = tid & 7;
;     const bf16* ap = A + (size_t)(m0 + arow) * K + ck * 8;
;     const bf16* bp = Bt + (size_t)(arow < 32 ? n0 + arow : n1 + arow - 32) * K + ck * 8;
;     const int soff = (arow * GS_LD + ck * 8) * 2;
;     f32x16 acc0, acc1;
; #pragma unroll
;     for (int i = 0; i < 16; ++i) { acc0[i] = 0.f; acc1[i] = 0.f; }
;     GsRegs<ROWS> R0, R1, R2, R3;
;     gs_load<ROWS>(R0, ap, bp, K, 0); gs_load<ROWS>(R1, ap, bp, K, 1); gs_load<ROWS>(R2, ap, bp, K, 2); gs_load<ROWS>(R3, ap, bp, K, 3);
;     gs_store<ROWS>(R0, lds, soff);
;     __syncthreads();
;     const int nkt = K >> 6;
;     ...
; #pragma unroll 1
;     for (int kt = 0; kt < nkt; kt += 4) { GS_STEP(R0, R1, kt); GS_STEP(R1, R2, kt + 1); GS_STEP(R2, R3, kt + 2); GS_STEP(R3, R0, kt + 3); }
.LBB0_2188:
	s_cmp_gt_u32 s81, 27
	s_cselect_b64 s[78:79], -1, 0
	s_cmp_lt_u32 s81, 28
	s_cselect_b32 s10, s80, 0x7c0
	s_lshl_b64 s[82:83], s[10:11], 1
	v_lshl_add_u64 v[4:5], v[74:75], 0, s[82:83]
	v_lshl_add_u64 v[8:9], v[76:77], 0, s[82:83]
	global_load_dwordx4 v[4:7], v[4:5], off
	s_nop 0
	global_load_dwordx4 v[8:11], v[8:9], off
	s_and_b64 vcc, exec, s[0:1]
	s_cbranch_vccnz .LBB0_2190
	ds_read_b128 v[12:15], v81
	ds_read_b128 v[82:85], v80 offset:9216
	ds_read_b128 v[86:89], v81 offset:32
	ds_read_b128 v[90:93], v80 offset:9248
	ds_read_b128 v[196:199], v80 offset:13824
	ds_read_b128 v[94:97], v80 offset:13856
	ds_read_b128 v[200:203], v81 offset:64
	ds_read_b128 v[204:207], v80 offset:9280
	ds_read_b128 v[208:211], v81 offset:96
	ds_read_b128 v[212:215], v80 offset:9312
	ds_read_b128 v[216:219], v80 offset:13888
	ds_read_b128 v[220:223], v80 offset:13920
	s_waitcnt lgkmcnt(10)
	v_mfma_f32_32x32x16_bf16 v[34:49], v[12:15], v[82:85], v[34:49]
	s_waitcnt lgkmcnt(7)
	v_mfma_f32_32x32x16_bf16 v[18:33], v[12:15], v[196:199], v[18:33]
	v_mfma_f32_32x32x16_bf16 v[34:49], v[86:89], v[90:93], v[34:49]
	s_waitcnt lgkmcnt(6)
	v_mfma_f32_32x32x16_bf16 v[18:33], v[86:89], v[94:97], v[18:33]
	s_waitcnt lgkmcnt(4)
	v_mfma_f32_32x32x16_bf16 v[34:49], v[200:203], v[204:207], v[34:49]
	s_waitcnt lgkmcnt(1)
	v_mfma_f32_32x32x16_bf16 v[18:33], v[200:203], v[216:219], v[18:33]
	v_mfma_f32_32x32x16_bf16 v[34:49], v[208:211], v[212:215], v[34:49]
	s_waitcnt lgkmcnt(0)
	v_mfma_f32_32x32x16_bf16 v[18:33], v[208:211], v[220:223], v[18:33]
.LBB0_2190:
	s_min_u32 s10, s81, 26
	s_lshl_b32 s10, s10, 7
	v_lshl_add_u64 v[12:13], v[74:75], 0, s[10:11]
	s_waitcnt vmcnt(7)
	ds_write_b128 v79, v[50:53] offset:18432
	s_waitcnt vmcnt(6)
	ds_write_b128 v79, v[54:57] offset:27648
	s_waitcnt lgkmcnt(0)
	s_barrier
	v_lshl_add_u64 v[14:15], v[76:77], 0, s[10:11]
	global_load_dwordx4 v[50:53], v[12:13], off offset:640
	global_load_dwordx4 v[54:57], v[14:15], off offset:640
	s_and_b64 vcc, exec, s[0:1]
	s_cbranch_vccnz .LBB0_2192
	ds_read_b128 v[12:15], v81 offset:18432
	ds_read_b128 v[82:85], v80 offset:27648
	ds_read_b128 v[86:89], v81 offset:18464
	ds_read_b128 v[90:93], v80 offset:27680
	ds_read_b128 v[196:199], v80 offset:32256
	ds_read_b128 v[94:97], v80 offset:32288
	ds_read_b128 v[200:203], v81 offset:18496
	ds_read_b128 v[204:207], v80 offset:27712
	ds_read_b128 v[208:211], v81 offset:18528
	ds_read_b128 v[212:215], v80 offset:27744
	ds_read_b128 v[216:219], v80 offset:32320
	ds_read_b128 v[220:223], v80 offset:32352
	s_waitcnt lgkmcnt(10)
	v_mfma_f32_32x32x16_bf16 v[34:49], v[12:15], v[82:85], v[34:49]
	s_waitcnt lgkmcnt(7)
	v_mfma_f32_32x32x16_bf16 v[18:33], v[12:15], v[196:199], v[18:33]
	v_mfma_f32_32x32x16_bf16 v[34:49], v[86:89], v[90:93], v[34:49]
	s_waitcnt lgkmcnt(6)
	v_mfma_f32_32x32x16_bf16 v[18:33], v[86:89], v[94:97], v[18:33]
	s_waitcnt lgkmcnt(4)
	v_mfma_f32_32x32x16_bf16 v[34:49], v[200:203], v[204:207], v[34:49]
	s_waitcnt lgkmcnt(1)
	v_mfma_f32_32x32x16_bf16 v[18:33], v[200:203], v[216:219], v[18:33]
	v_mfma_f32_32x32x16_bf16 v[34:49], v[208:211], v[212:215], v[34:49]
	s_waitcnt lgkmcnt(0)
	v_mfma_f32_32x32x16_bf16 v[18:33], v[208:211], v[220:223], v[18:33]
.LBB0_2192:
	s_min_u32 s10, s81, 25
	s_lshl_b32 s10, s10, 7
	v_lshl_add_u64 v[12:13], v[74:75], 0, s[10:11]
	s_waitcnt vmcnt(7)
	ds_write_b128 v79, v[58:61]
	s_waitcnt vmcnt(5)
	ds_write_b128 v79, v[66:69] offset:9216
	s_waitcnt lgkmcnt(0)
	s_barrier
	v_lshl_add_u64 v[14:15], v[76:77], 0, s[10:11]
	global_load_dwordx4 v[58:61], v[12:13], off offset:768
	global_load_dwordx4 v[66:69], v[14:15], off offset:768
	s_and_b64 vcc, exec, s[0:1]
	s_cbranch_vccnz .LBB0_2194
	ds_read_b128 v[12:15], v81
	ds_read_b128 v[82:85], v80 offset:9216
	ds_read_b128 v[86:89], v81 offset:32
	ds_read_b128 v[90:93], v80 offset:9248
	ds_read_b128 v[196:199], v80 offset:13824
	ds_read_b128 v[94:97], v80 offset:13856
	ds_read_b128 v[200:203], v81 offset:64
	ds_read_b128 v[204:207], v80 offset:9280
	ds_read_b128 v[208:211], v81 offset:96
	ds_read_b128 v[212:215], v80 offset:9312
	ds_read_b128 v[216:219], v80 offset:13888
	ds_read_b128 v[220:223], v80 offset:13920
	s_waitcnt lgkmcnt(10)
	v_mfma_f32_32x32x16_bf16 v[34:49], v[12:15], v[82:85], v[34:49]
	s_waitcnt lgkmcnt(7)
	v_mfma_f32_32x32x16_bf16 v[18:33], v[12:15], v[196:199], v[18:33]
	v_mfma_f32_32x32x16_bf16 v[34:49], v[86:89], v[90:93], v[34:49]
	s_waitcnt lgkmcnt(6)
	v_mfma_f32_32x32x16_bf16 v[18:33], v[86:89], v[94:97], v[18:33]
	s_waitcnt lgkmcnt(4)
	v_mfma_f32_32x32x16_bf16 v[34:49], v[200:203], v[204:207], v[34:49]
	s_waitcnt lgkmcnt(1)
	v_mfma_f32_32x32x16_bf16 v[18:33], v[200:203], v[216:219], v[18:33]
	v_mfma_f32_32x32x16_bf16 v[34:49], v[208:211], v[212:215], v[34:49]
	s_waitcnt lgkmcnt(0)
	v_mfma_f32_32x32x16_bf16 v[18:33], v[208:211], v[220:223], v[18:33]
.LBB0_2194:
	s_min_u32 s10, s81, 24
	s_lshl_b32 s10, s10, 7
	v_lshl_add_u64 v[12:13], v[74:75], 0, s[10:11]
	ds_write_b128 v79, v[62:65] offset:18432
	s_waitcnt vmcnt(6)
	ds_write_b128 v79, v[70:73] offset:27648
	s_waitcnt lgkmcnt(0)
	s_barrier
	v_lshl_add_u64 v[14:15], v[76:77], 0, s[10:11]
	global_load_dwordx4 v[62:65], v[12:13], off offset:896
	global_load_dwordx4 v[70:73], v[14:15], off offset:896
	s_and_b64 vcc, exec, s[0:1]
	s_cbranch_vccnz .LBB0_2187
	ds_read_b128 v[12:15], v81 offset:18432
	ds_read_b128 v[82:85], v80 offset:27648
	ds_read_b128 v[86:89], v81 offset:18464
	ds_read_b128 v[90:93], v80 offset:27680
	ds_read_b128 v[196:199], v80 offset:32256
	ds_read_b128 v[94:97], v80 offset:32288
	ds_read_b128 v[200:203], v81 offset:18496
	ds_read_b128 v[204:207], v80 offset:27712
	ds_read_b128 v[208:211], v81 offset:18528
	ds_read_b128 v[212:215], v80 offset:27744
	ds_read_b128 v[216:219], v80 offset:32320
	ds_read_b128 v[220:223], v80 offset:32352
	s_waitcnt lgkmcnt(10)
	v_mfma_f32_32x32x16_bf16 v[34:49], v[12:15], v[82:85], v[34:49]
	s_waitcnt lgkmcnt(7)
	v_mfma_f32_32x32x16_bf16 v[18:33], v[12:15], v[196:199], v[18:33]
	v_mfma_f32_32x32x16_bf16 v[34:49], v[86:89], v[90:93], v[34:49]
	s_waitcnt lgkmcnt(6)
	v_mfma_f32_32x32x16_bf16 v[18:33], v[86:89], v[94:97], v[18:33]
	s_waitcnt lgkmcnt(4)
	v_mfma_f32_32x32x16_bf16 v[34:49], v[200:203], v[204:207], v[34:49]
	s_waitcnt lgkmcnt(1)
	v_mfma_f32_32x32x16_bf16 v[18:33], v[200:203], v[216:219], v[18:33]
	v_mfma_f32_32x32x16_bf16 v[34:49], v[208:211], v[212:215], v[34:49]
	s_waitcnt lgkmcnt(0)
	v_mfma_f32_32x32x16_bf16 v[18:33], v[208:211], v[220:223], v[18:33]
	s_branch .LBB0_2187
